# v013 + z-gate loads issued at unit start next to the Q loads (MoBA and both NSA units), consumed in the epilogue
# baseline (speedup 1.0000x reference)
; __device__ __forceinline__ int fresh_tid(int wv) { return wv * 64 + fresh_lane(); }
; __device__ __forceinline__ unsigned cvtpk(float lo, float hi) { f32x2_t v = {lo, hi}; bf16x2_t b = __builtin_convertvector(v, bf16x2_t); return __builtin_bit_cast(unsigned, b); }
; __device__ __forceinline__ float sigmoidf_(float x) { return __builtin_amdgcn_rcpf(1.f + fexp2(-1.4426950408889634f * x)); }
; __device__ __forceinline__ void attn_epilogue(const f32x16& a0, const f32x16& a1, float scale, const bf16* zrow, bf16* orow, int hi) {
; #pragma unroll
;     for (int db = 0; db < 2; ++db)
; #pragma unroll
;         for (int p = 0; p < 2; ++p) {
;             const f32x16& o = db ? a1 : a0;
;             float x[4], y[4];
; #pragma unroll
;             for (int i = 0; i < 4; ++i) {
;                 auto rr = __builtin_amdgcn_permlane32_swap(__float_as_uint(o[8 * p + i]), __float_as_uint(o[8 * p + 4 + i]), false, false);
;                 x[i] = __uint_as_float(rr[0]); y[i] = __uint_as_float(rr[1]);
;             }
;             const int d = 32 * db + 8 * (2 * p + hi);
;             const v4u zz = *(const v4u*)(zrow + d);
;             f32x4 za, zb; unpack8(zz, za, zb);
;             float v[8];
; #pragma unroll
;             for (int i = 0; i < 4; ++i) { v[i] = x[i] * scale * za[i] * sigmoidf_(za[i]); v[4 + i] = y[i] * scale * zb[i] * sigmoidf_(zb[i]); }
;             *(v4u*)(orow + d) = (v4u){cvtpk(v[0], v[1]), cvtpk(v[2], v[3]), cvtpk(v[4], v[5]), cvtpk(v[6], v[7])};
;         }
; }
; __device__ __forceinline__ void nsa_unit(const int wv, LAS unsigned char* lds, int b, int g, int c, const bf16* Y, const bf16* KCMP, const bf16* VCMP, const float* gates, bf16* OG) {
;     ...
;         const float l = swap_sum(o2[0]); const float s = g2 / l;
; #pragma unroll
;         for (int r = 0; r < 16; ++r) { acc0[r] = accs[r * 512] + s * o0[r]; acc1[r] = accs[(16 + r) * 512] + s * o1[r]; }
;     }
;     const int tid3 = fresh_tid(wv); const int hi3 = (tid3 >> 5) & 1, hh3 = 4 * g + (tid3 >> 7); const size_t row3 = (size_t)b * T + 64 * c + 32 * ((tid3 >> 6) & 1) + (tid3 & 31);
;     attn_epilogue(acc0, acc1, 1.0f, Y + row3 * NSA_LDY + 2048 + hh3 * 64, OG + row3 * D + hh3 * 64, hi3);
.LBB0_839:
	v_mov_b32_e32 v32, v34
	s_nop 1
	v_permlane32_swap_b32_e32 v34, v32
	v_add_f32_e32 v32, v34, v32
	v_div_scale_f32 v33, s[0:1], v32, v32, v184
	v_rcp_f32_e32 v34, v33
	ds_read2st64_b32 v[40:41], v185 offset0:48 offset1:56
	ds_read2st64_b32 v[38:39], v185 offset1:8
	ds_read2st64_b32 v[42:43], v185 offset0:32 offset1:40
	v_fma_f32 v35, -v33, v34, 1.0
	v_fmac_f32_e32 v34, v35, v34
	v_div_scale_f32 v35, vcc, v184, v32, v184
	v_mul_f32_e32 v36, v35, v34
	v_fma_f32 v37, -v33, v36, v35
	v_fmac_f32_e32 v36, v37, v34
	v_fma_f32 v33, -v33, v36, v35
	v_div_fmas_f32 v33, v33, v34, v36
	ds_read2st64_b32 v[34:35], v185 offset0:128 offset1:136
	v_div_fixup_f32 v44, v33, v32, v184
	ds_read2st64_b32 v[36:37], v185 offset0:16 offset1:24
	ds_read2st64_b32 v[32:33], v185 offset0:144 offset1:152
	s_waitcnt lgkmcnt(5)
	v_fma_f32 v40, v6, v44, v40
	s_waitcnt lgkmcnt(2)
	v_fma_f32 v34, v16, v44, v34
	v_fmac_f32_e32 v35, v17, v44
	ds_read2st64_b32 v[16:17], v185 offset0:192 offset1:200
	s_waitcnt lgkmcnt(2)
	v_fma_f32 v36, v2, v44, v36
	v_fmac_f32_e32 v37, v3, v44
	ds_read2st64_b32 v[2:3], v185 offset0:176 offset1:184
	s_waitcnt lgkmcnt(2)
	v_fma_f32 v32, v18, v44, v32
	s_waitcnt lgkmcnt(1)
	v_fma_f32 v16, v24, v44, v16
	v_fmac_f32_e32 v17, v25, v44
	ds_read2st64_b32 v[24:25], v185 offset0:96 offset1:104
	v_fmac_f32_e32 v33, v19, v44
	ds_read2st64_b32 v[18:19], v185 offset0:160 offset1:168
	s_waitcnt lgkmcnt(2)
	v_fma_f32 v2, v22, v44, v2
	v_fmac_f32_e32 v41, v7, v44
	v_fmac_f32_e32 v3, v23, v44
	ds_read2st64_b32 v[22:23], v185 offset0:64 offset1:72
	ds_read2st64_b32 v[6:7], v185 offset0:208 offset1:216
	s_waitcnt lgkmcnt(3)
	v_fma_f32 v24, v12, v44, v24
	v_fmac_f32_e32 v25, v13, v44
	ds_read2st64_b32 v[12:13], v185 offset0:112 offset1:120
	v_fma_f32 v38, v0, v44, v38
	v_fma_f32 v42, v4, v44, v42
	s_waitcnt lgkmcnt(3)
	v_fma_f32 v18, v20, v44, v18
	v_fmac_f32_e32 v43, v5, v44
	v_fmac_f32_e32 v19, v21, v44
	s_waitcnt lgkmcnt(2)
	v_fma_f32 v22, v8, v44, v22
	v_fmac_f32_e32 v23, v9, v44
	ds_read2st64_b32 v[20:21], v185 offset0:80 offset1:88
	s_waitcnt lgkmcnt(2)
	v_fma_f32 v6, v26, v44, v6
	ds_read2st64_b32 v[8:9], v185 offset0:224 offset1:232
	ds_read2st64_b32 v[4:5], v185 offset0:240 offset1:248
	v_mbcnt_lo_u32_b32 v26, -1, 0
	v_mbcnt_hi_u32_b32 v26, -1, v26
	s_waitcnt lgkmcnt(3)
	v_fma_f32 v12, v14, v44, v12
	v_add_u32_e32 v0, s83, v26
	v_ashrrev_i32_e32 v14, 7, v0
	v_lshrrev_b32_e32 v0, 1, v0
	v_fmac_f32_e32 v39, v1, v44
	v_and_b32_e32 v0, 32, v0
	v_and_b32_e32 v1, 31, v26
	v_readlane_b32 s0, v255, 13
	s_waitcnt lgkmcnt(2)
	v_fma_f32 v20, v10, v44, v20
	v_fmac_f32_e32 v21, v11, v44
	v_or3_b32 v0, s0, v0, v1
	v_readlane_b32 s0, v254, 27
	v_readlane_b32 s1, v254, 28
	v_readlane_b32 s4, v255, 14
	v_fmac_f32_e32 v13, v15, v44
	v_mov_b64_e32 v[10:11], s[0:1]
	v_mad_u64_u32 v[10:11], s[0:1], v0, s84, v[10:11]
	v_readlane_b32 s0, v254, 21
	v_mov_b32_e32 v1, s4
	v_lshlrev_b64 v[0:1], 11, v[0:1]
	v_add_lshl_u32 v14, v14, s0, 6
	v_readlane_b32 s0, v254, 25
	v_ashrrev_i32_e32 v15, 31, v14
	v_readlane_b32 s1, v254, 26
	v_mad_i32_i24 v11, s4, v246, v11
	v_lshlrev_b64 v[14:15], 1, v[14:15]
	v_lshl_add_u64 v[0:1], s[0:1], 0, v[0:1]
	v_lshl_add_u64 v[10:11], v[10:11], 0, v[14:15]
	v_lshl_add_u64 v[14:15], v[0:1], 0, v[14:15]
	v_lshrrev_b32_e32 v0, 1, v26
	v_and_b32_e32 v114, 16, v0
	v_lshl_add_u64 v[10:11], v[10:11], 0, v[114:115]
	s_mov_b64 s[0:1], 0x1000
	v_lshl_add_u64 v[0:1], v[10:11], 0, s[0:1]
	s_movk_i32 s0, 0x1000
	v_add_co_u32_e32 v10, vcc, s0, v10
	v_fmac_f32_e32 v7, v27, v44
	s_nop 0
	v_addc_co_u32_e32 v11, vcc, 0, v11, vcc
	s_waitcnt lgkmcnt(1)
	v_fma_f32 v8, v28, v44, v8
	v_fmac_f32_e32 v9, v29, v44
	v_permlane32_swap_b32_e32 v38, v42
	v_permlane32_swap_b32_e32 v39, v43
	s_waitcnt lgkmcnt(0)
	v_fma_f32 v4, v30, v44, v4
	v_fmac_f32_e32 v5, v31, v44
	v_permlane32_swap_b32_e32 v36, v40
	v_permlane32_swap_b32_e32 v37, v41
	v_permlane32_swap_b32_e32 v22, v24
	v_permlane32_swap_b32_e32 v23, v25
	v_permlane32_swap_b32_e32 v20, v12
	v_permlane32_swap_b32_e32 v21, v13
	v_permlane32_swap_b32_e32 v34, v18
	v_permlane32_swap_b32_e32 v35, v19
	v_permlane32_swap_b32_e32 v32, v2
	v_permlane32_swap_b32_e32 v33, v3
	v_permlane32_swap_b32_e32 v16, v8
	v_permlane32_swap_b32_e32 v17, v9
	v_permlane32_swap_b32_e32 v6, v4
	v_permlane32_swap_b32_e32 v7, v5
	s_add_i32 s19, s19, 1
	s_cmp_eq_u32 s19, 4
	s_waitcnt vmcnt(3)
	v_lshlrev_b32_e32 v10, 16, v212
	v_and_b32_e32 v11, 0xffff0000, v212
	v_mul_f32_e32 v26, 0xbfb8aa3b, v10
	v_pk_mul_f32 v[38:39], v[38:39], v[10:11]
	v_mul_f32_e32 v10, 0xbfb8aa3b, v11
	v_exp_f32_e32 v26, v26
	v_exp_f32_e32 v10, v10
	v_add_f32_e32 v26, 1.0, v26
	v_add_f32_e32 v10, 1.0, v10
	v_rcp_f32_e32 v30, v26
	v_rcp_f32_e32 v31, v10
	s_nop 0
	v_pk_mul_f32 v[10:11], v[38:39], v[30:31]
	v_lshlrev_b32_e32 v30, 16, v214
	v_mul_f32_e32 v26, 0xbfb8aa3b, v30
	v_exp_f32_e32 v26, v26
	v_and_b32_e32 v31, 0xffff0000, v214
	v_pk_mul_f32 v[42:43], v[42:43], v[30:31]
	v_add_f32_e32 v26, 1.0, v26
	v_rcp_f32_e32 v38, v26
	v_mul_f32_e32 v26, 0xbfb8aa3b, v31
	v_exp_f32_e32 v26, v26
	s_nop 0
	v_add_f32_e32 v26, 1.0, v26
	v_rcp_f32_e32 v39, v26
	v_lshlrev_b32_e32 v26, 16, v213
	v_and_b32_e32 v27, 0xffff0000, v213
	v_mul_f32_e32 v28, 0xbfb8aa3b, v26
	v_pk_mul_f32 v[36:37], v[36:37], v[26:27]
	v_mul_f32_e32 v26, 0xbfb8aa3b, v27
	v_exp_f32_e32 v28, v28
	v_exp_f32_e32 v26, v26
	v_pk_mul_f32 v[30:31], v[42:43], v[38:39]
	v_and_b32_e32 v27, 0xffff0000, v215
	v_add_f32_e32 v28, 1.0, v28
	v_add_f32_e32 v26, 1.0, v26
	v_rcp_f32_e32 v38, v28
	v_rcp_f32_e32 v39, v26
	v_lshlrev_b32_e32 v26, 16, v215
	v_mul_f32_e32 v28, 0xbfb8aa3b, v26
	v_exp_f32_e32 v28, v28
	v_pk_mul_f32 v[36:37], v[36:37], v[38:39]
	v_pk_mul_f32 v[38:39], v[40:41], v[26:27]
	v_mul_f32_e32 v26, 0xbfb8aa3b, v27
	v_exp_f32_e32 v26, v26
	v_add_f32_e32 v28, 1.0, v28
	v_rcp_f32_e32 v28, v28
	v_cvt_pk_bf16_f32 v27, v36, v37
	v_add_f32_e32 v26, 1.0, v26
	v_rcp_f32_e32 v29, v26
	v_cvt_pk_bf16_f32 v26, v10, v11
	v_lshl_add_u64 v[10:11], v[14:15], 0, v[114:115]
	v_pk_mul_f32 v[38:39], v[38:39], v[28:29]
	v_cvt_pk_bf16_f32 v28, v30, v31
	v_cvt_pk_bf16_f32 v29, v38, v39
	global_store_dwordx4 v[10:11], v[26:29], off
	s_waitcnt vmcnt(3)
; __device__ __forceinline__ unsigned cvtpk(float lo, float hi) { f32x2_t v = {lo, hi}; bf16x2_t b = __builtin_convertvector(v, bf16x2_t); return __builtin_bit_cast(unsigned, b); }
; __device__ __forceinline__ float sigmoidf_(float x) { return __builtin_amdgcn_rcpf(1.f + fexp2(-1.4426950408889634f * x)); }
; __device__ __forceinline__ void attn_epilogue(const f32x16& a0, const f32x16& a1, float scale, const bf16* zrow, bf16* orow, int hi) {
; #pragma unroll
;     for (int db = 0; db < 2; ++db)
; #pragma unroll
;         for (int p = 0; p < 2; ++p) {
;             const f32x16& o = db ? a1 : a0;
;             float x[4], y[4];
; #pragma unroll
;             for (int i = 0; i < 4; ++i) {
;                 auto rr = __builtin_amdgcn_permlane32_swap(__float_as_uint(o[8 * p + i]), __float_as_uint(o[8 * p + 4 + i]), false, false);
;                 x[i] = __uint_as_float(rr[0]); y[i] = __uint_as_float(rr[1]);
;             }
;             const int d = 32 * db + 8 * (2 * p + hi);
;             const v4u zz = *(const v4u*)(zrow + d);
;             f32x4 za, zb; unpack8(zz, za, zb);
;             float v[8];
; #pragma unroll
;             for (int i = 0; i < 4; ++i) { v[i] = x[i] * scale * za[i] * sigmoidf_(za[i]); v[4 + i] = y[i] * scale * zb[i] * sigmoidf_(zb[i]); }
;             *(v4u*)(orow + d) = (v4u){cvtpk(v[0], v[1]), cvtpk(v[2], v[3]), cvtpk(v[4], v[5]), cvtpk(v[6], v[7])};
;         }
; }
	v_lshlrev_b32_e32 v14, 16, v216
	v_and_b32_e32 v15, 0xffff0000, v216
	v_mul_f32_e32 v26, 0xbfb8aa3b, v14
	v_pk_mul_f32 v[22:23], v[22:23], v[14:15]
	v_mul_f32_e32 v14, 0xbfb8aa3b, v15
	v_exp_f32_e32 v26, v26
	v_exp_f32_e32 v14, v14
	v_add_f32_e32 v26, 1.0, v26
	v_add_f32_e32 v14, 1.0, v14
	v_rcp_f32_e32 v30, v26
	v_rcp_f32_e32 v31, v14
	s_nop 0
	v_pk_mul_f32 v[14:15], v[22:23], v[30:31]
	v_lshlrev_b32_e32 v22, 16, v218
	v_and_b32_e32 v23, 0xffff0000, v218
	v_mul_f32_e32 v26, 0xbfb8aa3b, v22
	v_pk_mul_f32 v[24:25], v[24:25], v[22:23]
	v_mul_f32_e32 v22, 0xbfb8aa3b, v23
	v_exp_f32_e32 v26, v26
	v_exp_f32_e32 v22, v22
	v_add_f32_e32 v26, 1.0, v26
	v_add_f32_e32 v22, 1.0, v22
	v_rcp_f32_e32 v30, v26
	v_rcp_f32_e32 v31, v22
	s_nop 0
	v_pk_mul_f32 v[22:23], v[24:25], v[30:31]
	v_lshlrev_b32_e32 v24, 16, v217
	v_and_b32_e32 v25, 0xffff0000, v217
	v_mul_f32_e32 v26, 0xbfb8aa3b, v24
	v_pk_mul_f32 v[20:21], v[20:21], v[24:25]
	v_mul_f32_e32 v24, 0xbfb8aa3b, v25
	v_exp_f32_e32 v26, v26
	v_exp_f32_e32 v24, v24
	v_and_b32_e32 v25, 0xffff0000, v219
	v_add_f32_e32 v26, 1.0, v26
	v_add_f32_e32 v24, 1.0, v24
	v_rcp_f32_e32 v26, v26
	v_rcp_f32_e32 v27, v24
	v_lshlrev_b32_e32 v24, 16, v219
	v_pk_mul_f32 v[12:13], v[12:13], v[24:25]
	v_pk_mul_f32 v[20:21], v[20:21], v[26:27]
	v_mul_f32_e32 v26, 0xbfb8aa3b, v24
	v_mul_f32_e32 v24, 0xbfb8aa3b, v25
	v_exp_f32_e32 v26, v26
	v_exp_f32_e32 v24, v24
	v_add_f32_e32 v26, 1.0, v26
	v_add_f32_e32 v24, 1.0, v24
	v_rcp_f32_e32 v26, v26
	v_rcp_f32_e32 v27, v24
	s_nop 0
	v_pk_mul_f32 v[24:25], v[12:13], v[26:27]
	v_cvt_pk_bf16_f32 v12, v14, v15
	v_cvt_pk_bf16_f32 v13, v20, v21
	v_cvt_pk_bf16_f32 v14, v22, v23
	v_cvt_pk_bf16_f32 v15, v24, v25
	global_store_dwordx4 v[10:11], v[12:15], off offset:32
	s_waitcnt vmcnt(3)
	v_lshlrev_b32_e32 v20, 16, v220
	v_and_b32_e32 v21, 0xffff0000, v220
	v_mul_f32_e32 v12, 0xbfb8aa3b, v20
	v_exp_f32_e32 v12, v12
	v_pk_mul_f32 v[24:25], v[34:35], v[20:21]
	v_add_f32_e32 v12, 1.0, v12
	v_rcp_f32_e32 v22, v12
	v_mul_f32_e32 v12, 0xbfb8aa3b, v21
	v_exp_f32_e32 v12, v12
	s_nop 0
	v_add_f32_e32 v12, 1.0, v12
	v_rcp_f32_e32 v23, v12
	s_nop 0
	v_pk_mul_f32 v[20:21], v[24:25], v[22:23]
	v_lshlrev_b32_e32 v22, 16, v222
	v_mul_f32_e32 v12, 0xbfb8aa3b, v22
	v_exp_f32_e32 v12, v12
	v_and_b32_e32 v23, 0xffff0000, v222
	v_pk_mul_f32 v[18:19], v[18:19], v[22:23]
	v_add_f32_e32 v12, 1.0, v12
	v_rcp_f32_e32 v24, v12
	v_mul_f32_e32 v12, 0xbfb8aa3b, v23
	v_exp_f32_e32 v12, v12
	s_nop 0
	v_add_f32_e32 v12, 1.0, v12
	v_rcp_f32_e32 v25, v12
	v_lshlrev_b32_e32 v12, 16, v221
	v_and_b32_e32 v13, 0xffff0000, v221
	v_mul_f32_e32 v14, 0xbfb8aa3b, v12
	v_pk_mul_f32 v[18:19], v[18:19], v[24:25]
	v_pk_mul_f32 v[24:25], v[32:33], v[12:13]
	v_mul_f32_e32 v12, 0xbfb8aa3b, v13
	v_exp_f32_e32 v12, v12
	v_exp_f32_e32 v14, v14
	v_and_b32_e32 v13, 0xffff0000, v223
	v_add_f32_e32 v12, 1.0, v12
	v_add_f32_e32 v14, 1.0, v14
	v_rcp_f32_e32 v23, v12
	v_lshlrev_b32_e32 v12, 16, v223
	v_rcp_f32_e32 v22, v14
	v_mul_f32_e32 v14, 0xbfb8aa3b, v12
	v_pk_mul_f32 v[2:3], v[2:3], v[12:13]
	v_mul_f32_e32 v12, 0xbfb8aa3b, v13
	v_exp_f32_e32 v14, v14
	v_exp_f32_e32 v12, v12
	v_pk_mul_f32 v[22:23], v[24:25], v[22:23]
	v_add_f32_e32 v14, 1.0, v14
	v_add_f32_e32 v12, 1.0, v12
	v_rcp_f32_e32 v14, v14
	v_rcp_f32_e32 v15, v12
	v_cvt_pk_bf16_f32 v12, v20, v21
	v_cvt_pk_bf16_f32 v13, v22, v23
	v_pk_mul_f32 v[2:3], v[2:3], v[14:15]
	s_nop 0
	v_cvt_pk_bf16_f32 v15, v2, v3
	v_cvt_pk_bf16_f32 v14, v18, v19
	global_store_dwordx4 v[10:11], v[12:15], off offset:64
	s_waitcnt vmcnt(3)
	s_nop 0
	v_lshlrev_b32_e32 v12, 16, v224
	v_and_b32_e32 v13, 0xffff0000, v224
	v_mul_f32_e32 v0, 0xbfb8aa3b, v12
	v_exp_f32_e32 v0, v0
	v_pk_mul_f32 v[16:17], v[16:17], v[12:13]
	v_add_f32_e32 v0, 1.0, v0
	v_rcp_f32_e32 v14, v0
	v_mul_f32_e32 v0, 0xbfb8aa3b, v13
	v_exp_f32_e32 v0, v0
	s_nop 0
	v_add_f32_e32 v0, 1.0, v0
	v_rcp_f32_e32 v15, v0
	s_nop 0
	v_pk_mul_f32 v[12:13], v[16:17], v[14:15]
	v_lshlrev_b32_e32 v14, 16, v226
	v_mul_f32_e32 v0, 0xbfb8aa3b, v14
	v_exp_f32_e32 v0, v0
	v_and_b32_e32 v15, 0xffff0000, v226
	v_pk_mul_f32 v[8:9], v[8:9], v[14:15]
	v_add_f32_e32 v0, 1.0, v0
	v_rcp_f32_e32 v16, v0
	v_mul_f32_e32 v0, 0xbfb8aa3b, v15
	v_exp_f32_e32 v0, v0
	s_nop 0
	v_add_f32_e32 v0, 1.0, v0
	v_rcp_f32_e32 v17, v0
	v_lshlrev_b32_e32 v0, 16, v225
	v_and_b32_e32 v1, 0xffff0000, v225
	v_mul_f32_e32 v2, 0xbfb8aa3b, v0
	v_pk_mul_f32 v[6:7], v[6:7], v[0:1]
	v_mul_f32_e32 v0, 0xbfb8aa3b, v1
	v_exp_f32_e32 v0, v0
	v_exp_f32_e32 v2, v2
	v_and_b32_e32 v1, 0xffff0000, v227
	v_pk_mul_f32 v[8:9], v[8:9], v[16:17]
	v_add_f32_e32 v0, 1.0, v0
	v_add_f32_e32 v2, 1.0, v2
	v_rcp_f32_e32 v15, v0
	v_lshlrev_b32_e32 v0, 16, v227
	v_rcp_f32_e32 v14, v2
	v_mul_f32_e32 v2, 0xbfb8aa3b, v0
	v_pk_mul_f32 v[4:5], v[4:5], v[0:1]
	v_mul_f32_e32 v0, 0xbfb8aa3b, v1
	v_exp_f32_e32 v2, v2
	v_exp_f32_e32 v0, v0
	v_pk_mul_f32 v[6:7], v[6:7], v[14:15]
	v_add_f32_e32 v2, 1.0, v2
	v_add_f32_e32 v0, 1.0, v0
	v_rcp_f32_e32 v2, v2
	v_rcp_f32_e32 v3, v0
	v_cvt_pk_bf16_f32 v0, v12, v13
	v_cvt_pk_bf16_f32 v1, v6, v7
	v_pk_mul_f32 v[4:5], v[4:5], v[2:3]
	v_cvt_pk_bf16_f32 v2, v8, v9
	v_cvt_pk_bf16_f32 v3, v4, v5
	global_store_dwordx4 v[10:11], v[0:3], off offset:96
	s_barrier
	s_cbranch_scc1 .LBB0_1152

; #define LAS __attribute__((address_space(3)))
; template <bool HAS_POST, class MaskF>
; __device__ __forceinline__ void attn_run(LAS unsigned char* lds, const bf16* Kg, const bf16* Vg, int pitch, int t0, int t1,
;                                          const bf16x8 (&qr)[4], f32x16& o0, f32x16& o1, f32x16& o2, MaskF& mf, const int wv) {
;     const int tid_ = fresh_tid(wv);
;     const int tid = tid_, lane = tid & 63, r32 = lane & 31, hi = lane >> 5;
;     if (t0 >= t1) return;
;     const int lrow = tid >> 3, lch = tid & 7;
;     const unsigned kwoff = lrow * 144 + lch * 16;
;     const unsigned vwoff = ATT_V0 + lrow * 128 + (((lch >> 1) ^ (((lrow >> 1) & 1) << 1)) * 32) + (lch & 1) * 16;
;     const bf16* kp = Kg + (size_t)(64 * t0 + lrow) * pitch + lch * 8;
;     const bf16* vp = Vg + (size_t)(64 * t0 + lrow) * pitch + lch * 8;
;     const size_t tstride = (size_t)64 * pitch;
;     const v4u z4 = (v4u){0u, 0u, 0u, 0u};
;     v4u kreg0 = *(const v4u*)kp, kreg1 = z4, vreg0 = *(const v4u*)vp, vreg1 = z4;
; __device__ __forceinline__ void nsa_unit(const int wv, LAS unsigned char* lds, int b, int g, int c, const bf16* Y, const bf16* KCMP, const bf16* VCMP, const float* gates, bf16* OG) {
;     ...
;     const int tid = tid_, lane = tid & 63, r32 = lane & 31, hi = lane >> 5, wid = tid >> 6;
;     const int hr = wid >> 1, tq = 32 * (wid & 1) + r32, tabs = 64 * c + tq, hh = 4 * g + hr;
;     LAS float* imph = (LAS float*)(lds + LDS_IMP);
;     LAS unsigned long long* selm = (LAS unsigned long long*)(lds + LDS_SEL);
;     for (int i = tid; i < 4 * 64 * 65; i += NTHREADS) imph[i] = 0.f;
;     __syncthreads();
;     const size_t row = (size_t)b * T + tabs;
;     bf16x8 qr[4]; load_q(Y + row * NSA_LDY + hh * 64, hi, qr);
;     const float* gp = gates + row * 48 + hh * 3; const float g0 = gp[0], g1 = gp[1], g2 = gp[2];
;     f32x16 acc0 = zero16(), acc1 = zero16();
;     LAS float* invl = (LAS float*)(lds + LDS_SEL + 512);
;     {
;         int ncnt = 4 * c + 3; if (ncnt > 255) ncnt = 255; const int nct = (ncnt + 63) >> 6;
;         CmpMask mf; mf.tabs = tabs; mf.hi = hi; mf.imp = imph + (hr * 64 + tq) * 65;
;         const bf16* Kg = KCMP + (size_t)(b * 4 + g) * 256 * 64; const bf16* Vg = VCMP + (size_t)(b * 4 + g) * 256 * 64;
;         f32x16 o0 = zero16(), o1 = zero16(), o2 = zero16();
;         attn_run<true>(lds, Kg, Vg, 64, 0, nct, qr, o0, o1, o2, mf, wv);
.LBB0_843:
	s_or_b64 exec, exec, s[4:5]
	v_lshrrev_b32_e32 v0, 1, v160
	v_and_b32_e32 v2, 31, v33
	v_and_b32_e32 v3, 32, v0
	v_or_b32_e32 v158, v3, v2
	v_readlane_b32 s0, v254, 57
	v_ashrrev_i32_e32 v8, 7, v160
	v_bfe_u32 v159, v33, 5, 1
	v_or_b32_e32 v152, s0, v158
	s_lshl_b32 s0, s19, 2
	v_writelane_b32 v254, s0, 21
	v_add_u32_e32 v9, s0, v8
	v_readlane_b32 s0, v254, 9
	v_ashrrev_i32_e32 v153, 31, v152
	v_readlane_b32 s1, v254, 10
	v_lshlrev_b32_e32 v6, 6, v9
	v_ashrrev_i32_e32 v7, 31, v6
	v_lshl_add_u64 v[0:1], s[0:1], 0, v[152:153]
	v_readlane_b32 s0, v254, 27
	v_readlane_b32 s1, v254, 28
	v_lshlrev_b32_e32 v114, 4, v159
	s_waitcnt lgkmcnt(0)
	v_mov_b64_e32 v[4:5], s[0:1]
	v_mad_u64_u32 v[4:5], s[0:1], v0, s84, v[4:5]
	v_mad_i32_i24 v5, v1, s84, v5
	v_lshl_add_u64 v[4:5], v[6:7], 1, v[4:5]
	v_readlane_b32 s0, v254, 35
	v_lshl_add_u64 v[4:5], v[4:5], 0, v[114:115]
	v_readlane_b32 s1, v254, 36
	s_barrier
	global_load_dwordx4 v[116:119], v[4:5], off
	global_load_dwordx4 v[120:123], v[4:5], off offset:32
	global_load_dwordx4 v[124:127], v[4:5], off offset:64
	global_load_dwordx4 v[128:131], v[4:5], off offset:96
	v_add_co_u32_e32 v210, vcc, 0x1000, v4
	s_nop 1
	v_addc_co_u32_e32 v211, vcc, 0, v5, vcc
	global_load_dwordx4 v[212:215], v[210:211], off
	global_load_dwordx4 v[216:219], v[210:211], off offset:32
	global_load_dwordx4 v[220:223], v[210:211], off offset:64
	global_load_dwordx4 v[224:227], v[210:211], off offset:96
	v_mov_b64_e32 v[4:5], s[0:1]
	s_movk_i32 s4, 0xc0
	v_mad_u64_u32 v[4:5], s[0:1], v0, s4, v[4:5]
	v_lshl_add_u32 v0, v9, 1, v9
	v_mad_i32_i24 v5, v1, s4, v5
	v_ashrrev_i32_e32 v1, 31, v0
	v_lshl_add_u64 v[0:1], v[0:1], 2, v[4:5]
	global_load_dwordx3 v[182:184], v[0:1], off
	v_mov_b32_e32 v0, v115
	v_readlane_b32 s0, v254, 37
	v_mov_b32_e32 v0, v115
	v_readlane_b32 s1, v254, 38
	v_lshlrev_b32_e32 v153, 6, v8
	v_mov_b32_e32 v161, v115
	v_mov_b32_e32 v162, v115
	v_mov_b32_e32 v32, v115
	s_mov_b64 s[4:5], -1
	s_and_b64 vcc, exec, s[0:1]
	v_mbcnt_lo_u32_b32 v4, -1, 0
	v_mbcnt_hi_u32_b32 v4, -1, v4
	s_cbranch_vccz .LBB0_878
	s_lshl_b32 s0, s19, 14
	v_readlane_b32 s1, v254, 39
	s_add_i32 s0, s0, s1
	s_lshl_b32 s4, s0, 1
	v_readlane_b32 s0, v254, 33
	v_add_u32_e32 v5, s83, v4
	s_add_u32 s0, s0, s4
	v_readlane_b32 s1, v254, 34
	s_addc_u32 s1, s1, 0
	v_readlane_b32 s5, v254, 31
	v_ashrrev_i32_e32 v0, 3, v5
	s_add_u32 s4, s5, s4
	v_readlane_b32 s5, v254, 32
	v_ashrrev_i32_e32 v1, 31, v0
	s_addc_u32 s5, s5, 0
	v_and_b32_e32 v6, 7, v4
	v_lshlrev_b64 v[8:9], 7, v[0:1]
	v_lshl_add_u64 v[10:11], s[4:5], 0, v[8:9]
	v_lshlrev_b32_e32 v114, 4, v6
	v_lshl_add_u64 v[154:155], v[10:11], 0, v[114:115]
	v_lshl_add_u64 v[8:9], s[0:1], 0, v[8:9]
	v_lshl_add_u64 v[156:157], v[8:9], 0, v[114:115]
	global_load_dwordx4 v[82:85], v[154:155], off
	global_load_dwordx4 v[86:89], v[156:157], off
	v_readlane_b32 s0, v254, 40
	v_readlane_b32 s1, v254, 41
	s_andn2_b64 vcc, exec, s[0:1]
	s_cbranch_vccnz .LBB0_846
	v_add_co_u32_e32 v8, vcc, 0x2000, v154
	s_nop 1
	v_addc_co_u32_e32 v9, vcc, 0, v155, vcc
	v_add_co_u32_e32 v10, vcc, 0x2000, v156
	s_nop 1
	v_addc_co_u32_e32 v11, vcc, 0, v157, vcc
	global_load_dwordx4 v[90:93], v[8:9], off
	global_load_dwordx4 v[94:97], v[10:11], off
	s_branch .LBB0_847

; __device__ __forceinline__ int fresh_tid(int wv) { return wv * 64 + fresh_lane(); }
; __device__ __forceinline__ unsigned cvtpk(float lo, float hi) { f32x2_t v = {lo, hi}; bf16x2_t b = __builtin_convertvector(v, bf16x2_t); return __builtin_bit_cast(unsigned, b); }
; __device__ __forceinline__ float sigmoidf_(float x) { return __builtin_amdgcn_rcpf(1.f + fexp2(-1.4426950408889634f * x)); }
; __device__ __forceinline__ void attn_epilogue(const f32x16& a0, const f32x16& a1, float scale, const bf16* zrow, bf16* orow, int hi) {
; #pragma unroll
;     for (int db = 0; db < 2; ++db)
; #pragma unroll
;         for (int p = 0; p < 2; ++p) {
;             const f32x16& o = db ? a1 : a0;
;             float x[4], y[4];
; #pragma unroll
;             for (int i = 0; i < 4; ++i) {
;                 auto rr = __builtin_amdgcn_permlane32_swap(__float_as_uint(o[8 * p + i]), __float_as_uint(o[8 * p + 4 + i]), false, false);
;                 x[i] = __uint_as_float(rr[0]); y[i] = __uint_as_float(rr[1]);
;             }
;             const int d = 32 * db + 8 * (2 * p + hi);
;             const v4u zz = *(const v4u*)(zrow + d);
;             f32x4 za, zb; unpack8(zz, za, zb);
;             float v[8];
; #pragma unroll
;             for (int i = 0; i < 4; ++i) { v[i] = x[i] * scale * za[i] * sigmoidf_(za[i]); v[4 + i] = y[i] * scale * zb[i] * sigmoidf_(zb[i]); }
;             *(v4u*)(orow + d) = (v4u){cvtpk(v[0], v[1]), cvtpk(v[2], v[3]), cvtpk(v[4], v[5]), cvtpk(v[6], v[7])};
;         }
; }
; __device__ __forceinline__ void nsa_unit(const int wv, LAS unsigned char* lds, int b, int g, int c, const bf16* Y, const bf16* KCMP, const bf16* VCMP, const float* gates, bf16* OG) {
;     ...
;         const float l = swap_sum(o2[0]); const float s = g2 / l;
; #pragma unroll
;         for (int r = 0; r < 16; ++r) { acc0[r] = accs[r * 512] + s * o0[r]; acc1[r] = accs[(16 + r) * 512] + s * o1[r]; }
;     }
;     const int tid3 = fresh_tid(wv); const int hi3 = (tid3 >> 5) & 1, hh3 = 4 * g + (tid3 >> 7); const size_t row3 = (size_t)b * T + 64 * c + 32 * ((tid3 >> 6) & 1) + (tid3 & 31);
;     attn_epilogue(acc0, acc1, 1.0f, Y + row3 * NSA_LDY + 2048 + hh3 * 64, OG + row3 * D + hh3 * 64, hi3);
.LBB0_996:
	v_mov_b32_e32 v32, v34
	s_nop 1
	v_permlane32_swap_b32_e32 v34, v32
	v_add_f32_e32 v32, v34, v32
	v_div_scale_f32 v33, s[0:1], v32, v32, v184
	v_rcp_f32_e32 v34, v33
	ds_read2st64_b32 v[40:41], v185 offset0:48 offset1:56
	ds_read2st64_b32 v[38:39], v185 offset1:8
	ds_read2st64_b32 v[42:43], v185 offset0:32 offset1:40
	v_fma_f32 v35, -v33, v34, 1.0
	v_fmac_f32_e32 v34, v35, v34
	v_div_scale_f32 v35, vcc, v184, v32, v184
	v_mul_f32_e32 v36, v35, v34
	v_fma_f32 v37, -v33, v36, v35
	v_fmac_f32_e32 v36, v37, v34
	v_fma_f32 v33, -v33, v36, v35
	v_div_fmas_f32 v33, v33, v34, v36
	ds_read2st64_b32 v[34:35], v185 offset0:128 offset1:136
	v_div_fixup_f32 v44, v33, v32, v184
	ds_read2st64_b32 v[36:37], v185 offset0:16 offset1:24
	ds_read2st64_b32 v[32:33], v185 offset0:144 offset1:152
	s_waitcnt lgkmcnt(5)
	v_fma_f32 v40, v6, v44, v40
	s_waitcnt lgkmcnt(2)
	v_fma_f32 v34, v16, v44, v34
	v_fmac_f32_e32 v35, v17, v44
	ds_read2st64_b32 v[16:17], v185 offset0:192 offset1:200
	s_waitcnt lgkmcnt(2)
	v_fma_f32 v36, v2, v44, v36
	v_fmac_f32_e32 v37, v3, v44
	ds_read2st64_b32 v[2:3], v185 offset0:176 offset1:184
	s_waitcnt lgkmcnt(2)
	v_fma_f32 v32, v18, v44, v32
	s_waitcnt lgkmcnt(1)
	v_fma_f32 v16, v24, v44, v16
	v_fmac_f32_e32 v17, v25, v44
	ds_read2st64_b32 v[24:25], v185 offset0:96 offset1:104
	v_fmac_f32_e32 v33, v19, v44
	ds_read2st64_b32 v[18:19], v185 offset0:160 offset1:168
	s_waitcnt lgkmcnt(2)
	v_fma_f32 v2, v22, v44, v2
	v_fmac_f32_e32 v41, v7, v44
	v_fmac_f32_e32 v3, v23, v44
	ds_read2st64_b32 v[22:23], v185 offset0:64 offset1:72
	ds_read2st64_b32 v[6:7], v185 offset0:208 offset1:216
	s_waitcnt lgkmcnt(3)
	v_fma_f32 v24, v12, v44, v24
	v_fmac_f32_e32 v25, v13, v44
	ds_read2st64_b32 v[12:13], v185 offset0:112 offset1:120
	v_fma_f32 v38, v0, v44, v38
	v_fma_f32 v42, v4, v44, v42
	s_waitcnt lgkmcnt(3)
	v_fma_f32 v18, v20, v44, v18
	v_fmac_f32_e32 v43, v5, v44
	v_fmac_f32_e32 v19, v21, v44
	s_waitcnt lgkmcnt(2)
	v_fma_f32 v22, v8, v44, v22
	v_fmac_f32_e32 v23, v9, v44
	ds_read2st64_b32 v[20:21], v185 offset0:80 offset1:88
	s_waitcnt lgkmcnt(2)
	v_fma_f32 v6, v26, v44, v6
	ds_read2st64_b32 v[8:9], v185 offset0:224 offset1:232
	ds_read2st64_b32 v[4:5], v185 offset0:240 offset1:248
	v_mbcnt_lo_u32_b32 v26, -1, 0
	v_mbcnt_hi_u32_b32 v26, -1, v26
	s_waitcnt lgkmcnt(3)
	v_fma_f32 v12, v14, v44, v12
	v_add_u32_e32 v0, s83, v26
	v_ashrrev_i32_e32 v14, 7, v0
	v_lshrrev_b32_e32 v0, 1, v0
	v_fmac_f32_e32 v39, v1, v44
	v_and_b32_e32 v0, 32, v0
	v_and_b32_e32 v1, 31, v26
	v_readlane_b32 s0, v254, 58
	s_waitcnt lgkmcnt(2)
	v_fma_f32 v20, v10, v44, v20
	v_fmac_f32_e32 v21, v11, v44
	v_or3_b32 v0, s0, v0, v1
	v_readlane_b32 s0, v254, 27
	v_readlane_b32 s1, v254, 28
	v_readlane_b32 s4, v254, 59
	v_fmac_f32_e32 v13, v15, v44
	v_mov_b64_e32 v[10:11], s[0:1]
	v_mad_u64_u32 v[10:11], s[0:1], v0, s84, v[10:11]
	v_readlane_b32 s0, v254, 21
	v_mov_b32_e32 v1, s4
	v_lshlrev_b64 v[0:1], 11, v[0:1]
	v_add_lshl_u32 v14, v14, s0, 6
	v_readlane_b32 s0, v254, 25
	v_ashrrev_i32_e32 v15, 31, v14
	v_readlane_b32 s1, v254, 26
	v_mad_i32_i24 v11, s4, v246, v11
	v_lshlrev_b64 v[14:15], 1, v[14:15]
	v_lshl_add_u64 v[0:1], s[0:1], 0, v[0:1]
	v_lshl_add_u64 v[10:11], v[10:11], 0, v[14:15]
	v_lshl_add_u64 v[14:15], v[0:1], 0, v[14:15]
	v_lshrrev_b32_e32 v0, 1, v26
	v_and_b32_e32 v114, 16, v0
	v_lshl_add_u64 v[10:11], v[10:11], 0, v[114:115]
	s_mov_b64 s[0:1], 0x1000
	v_lshl_add_u64 v[0:1], v[10:11], 0, s[0:1]
	s_movk_i32 s0, 0x1000
	v_add_co_u32_e32 v10, vcc, s0, v10
	v_fmac_f32_e32 v7, v27, v44
	s_nop 0
	v_addc_co_u32_e32 v11, vcc, 0, v11, vcc
	s_waitcnt lgkmcnt(1)
	v_fma_f32 v8, v28, v44, v8
	v_fmac_f32_e32 v9, v29, v44
	v_permlane32_swap_b32_e32 v38, v42
	v_permlane32_swap_b32_e32 v39, v43
	s_waitcnt lgkmcnt(0)
	v_fma_f32 v4, v30, v44, v4
	v_fmac_f32_e32 v5, v31, v44
	v_permlane32_swap_b32_e32 v36, v40
	v_permlane32_swap_b32_e32 v37, v41
	v_permlane32_swap_b32_e32 v22, v24
	v_permlane32_swap_b32_e32 v23, v25
	v_permlane32_swap_b32_e32 v20, v12
	v_permlane32_swap_b32_e32 v21, v13
	v_permlane32_swap_b32_e32 v34, v18
	v_permlane32_swap_b32_e32 v35, v19
	v_permlane32_swap_b32_e32 v32, v2
	v_permlane32_swap_b32_e32 v33, v3
	v_permlane32_swap_b32_e32 v16, v8
	v_permlane32_swap_b32_e32 v17, v9
	v_permlane32_swap_b32_e32 v6, v4
	v_permlane32_swap_b32_e32 v7, v5
	s_movk_i32 s0, 0x4100
	s_waitcnt vmcnt(3)
	v_lshlrev_b32_e32 v10, 16, v212
	v_and_b32_e32 v11, 0xffff0000, v212
	v_mul_f32_e32 v26, 0xbfb8aa3b, v10
	v_pk_mul_f32 v[38:39], v[38:39], v[10:11]
	v_mul_f32_e32 v10, 0xbfb8aa3b, v11
	v_exp_f32_e32 v26, v26
	v_exp_f32_e32 v10, v10
	v_add_f32_e32 v26, 1.0, v26
	v_add_f32_e32 v10, 1.0, v10
	v_rcp_f32_e32 v30, v26
	v_rcp_f32_e32 v31, v10
	s_nop 0
	v_pk_mul_f32 v[10:11], v[38:39], v[30:31]
	v_lshlrev_b32_e32 v30, 16, v214
	v_mul_f32_e32 v26, 0xbfb8aa3b, v30
	v_exp_f32_e32 v26, v26
	v_and_b32_e32 v31, 0xffff0000, v214
	v_pk_mul_f32 v[42:43], v[42:43], v[30:31]
	v_add_f32_e32 v26, 1.0, v26
	v_rcp_f32_e32 v38, v26
	v_mul_f32_e32 v26, 0xbfb8aa3b, v31
	v_exp_f32_e32 v26, v26
	s_nop 0
	v_add_f32_e32 v26, 1.0, v26
	v_rcp_f32_e32 v39, v26
	v_lshlrev_b32_e32 v26, 16, v213
	v_and_b32_e32 v27, 0xffff0000, v213
	v_mul_f32_e32 v28, 0xbfb8aa3b, v26
	v_pk_mul_f32 v[36:37], v[36:37], v[26:27]
	v_mul_f32_e32 v26, 0xbfb8aa3b, v27
	v_exp_f32_e32 v28, v28
	v_exp_f32_e32 v26, v26
	v_pk_mul_f32 v[30:31], v[42:43], v[38:39]
	v_and_b32_e32 v27, 0xffff0000, v215
	v_add_f32_e32 v28, 1.0, v28
	v_add_f32_e32 v26, 1.0, v26
	v_rcp_f32_e32 v38, v28
	v_rcp_f32_e32 v39, v26
	v_lshlrev_b32_e32 v26, 16, v215
	v_mul_f32_e32 v28, 0xbfb8aa3b, v26
	v_exp_f32_e32 v28, v28
	v_pk_mul_f32 v[36:37], v[36:37], v[38:39]
	v_pk_mul_f32 v[38:39], v[40:41], v[26:27]
	v_mul_f32_e32 v26, 0xbfb8aa3b, v27
	v_exp_f32_e32 v26, v26
	v_add_f32_e32 v28, 1.0, v28
	v_rcp_f32_e32 v28, v28
	v_cvt_pk_bf16_f32 v27, v36, v37
	v_add_f32_e32 v26, 1.0, v26
	v_rcp_f32_e32 v29, v26
	v_cvt_pk_bf16_f32 v26, v10, v11
	v_lshl_add_u64 v[10:11], v[14:15], 0, v[114:115]
	v_pk_mul_f32 v[38:39], v[38:39], v[28:29]
	v_cvt_pk_bf16_f32 v28, v30, v31
	v_cvt_pk_bf16_f32 v29, v38, v39
	global_store_dwordx4 v[10:11], v[26:29], off
	s_waitcnt vmcnt(3)
; __device__ __forceinline__ unsigned cvtpk(float lo, float hi) { f32x2_t v = {lo, hi}; bf16x2_t b = __builtin_convertvector(v, bf16x2_t); return __builtin_bit_cast(unsigned, b); }
; __device__ __forceinline__ float sigmoidf_(float x) { return __builtin_amdgcn_rcpf(1.f + fexp2(-1.4426950408889634f * x)); }
; __device__ __forceinline__ void attn_epilogue(const f32x16& a0, const f32x16& a1, float scale, const bf16* zrow, bf16* orow, int hi) {
; #pragma unroll
;     for (int db = 0; db < 2; ++db)
; #pragma unroll
;         for (int p = 0; p < 2; ++p) {
;             const f32x16& o = db ? a1 : a0;
;             float x[4], y[4];
; #pragma unroll
;             for (int i = 0; i < 4; ++i) {
;                 auto rr = __builtin_amdgcn_permlane32_swap(__float_as_uint(o[8 * p + i]), __float_as_uint(o[8 * p + 4 + i]), false, false);
;                 x[i] = __uint_as_float(rr[0]); y[i] = __uint_as_float(rr[1]);
;             }
;             const int d = 32 * db + 8 * (2 * p + hi);
;             const v4u zz = *(const v4u*)(zrow + d);
;             f32x4 za, zb; unpack8(zz, za, zb);
;             float v[8];
; #pragma unroll
;             for (int i = 0; i < 4; ++i) { v[i] = x[i] * scale * za[i] * sigmoidf_(za[i]); v[4 + i] = y[i] * scale * zb[i] * sigmoidf_(zb[i]); }
;             *(v4u*)(orow + d) = (v4u){cvtpk(v[0], v[1]), cvtpk(v[2], v[3]), cvtpk(v[4], v[5]), cvtpk(v[6], v[7])};
;         }
; }
; __device__ __forceinline__ void nsa_unit(const int wv, LAS unsigned char* lds, int b, int g, int c, const bf16* Y, const bf16* KCMP, const bf16* VCMP, const float* gates, bf16* OG) {
;     ...
;     for (int i = tid; i < 4 * 64 * 65; i += NTHREADS) imph[i] = 0.f;
	v_lshlrev_b32_e32 v14, 16, v216
	v_and_b32_e32 v15, 0xffff0000, v216
	v_mul_f32_e32 v26, 0xbfb8aa3b, v14
	v_pk_mul_f32 v[22:23], v[22:23], v[14:15]
	v_mul_f32_e32 v14, 0xbfb8aa3b, v15
	v_exp_f32_e32 v26, v26
	v_exp_f32_e32 v14, v14
	v_add_f32_e32 v26, 1.0, v26
	v_add_f32_e32 v14, 1.0, v14
	v_rcp_f32_e32 v30, v26
	v_rcp_f32_e32 v31, v14
	s_nop 0
	v_pk_mul_f32 v[14:15], v[22:23], v[30:31]
	v_lshlrev_b32_e32 v22, 16, v218
	v_and_b32_e32 v23, 0xffff0000, v218
	v_mul_f32_e32 v26, 0xbfb8aa3b, v22
	v_pk_mul_f32 v[24:25], v[24:25], v[22:23]
	v_mul_f32_e32 v22, 0xbfb8aa3b, v23
	v_exp_f32_e32 v26, v26
	v_exp_f32_e32 v22, v22
	v_add_f32_e32 v26, 1.0, v26
	v_add_f32_e32 v22, 1.0, v22
	v_rcp_f32_e32 v30, v26
	v_rcp_f32_e32 v31, v22
	s_nop 0
	v_pk_mul_f32 v[22:23], v[24:25], v[30:31]
	v_lshlrev_b32_e32 v24, 16, v217
	v_and_b32_e32 v25, 0xffff0000, v217
	v_mul_f32_e32 v26, 0xbfb8aa3b, v24
	v_pk_mul_f32 v[20:21], v[20:21], v[24:25]
	v_mul_f32_e32 v24, 0xbfb8aa3b, v25
	v_exp_f32_e32 v26, v26
	v_exp_f32_e32 v24, v24
	v_and_b32_e32 v25, 0xffff0000, v219
	v_add_f32_e32 v26, 1.0, v26
	v_add_f32_e32 v24, 1.0, v24
	v_rcp_f32_e32 v26, v26
	v_rcp_f32_e32 v27, v24
	v_lshlrev_b32_e32 v24, 16, v219
	v_pk_mul_f32 v[12:13], v[12:13], v[24:25]
	v_pk_mul_f32 v[20:21], v[20:21], v[26:27]
	v_mul_f32_e32 v26, 0xbfb8aa3b, v24
	v_mul_f32_e32 v24, 0xbfb8aa3b, v25
	v_exp_f32_e32 v26, v26
	v_exp_f32_e32 v24, v24
	v_add_f32_e32 v26, 1.0, v26
	v_add_f32_e32 v24, 1.0, v24
	v_rcp_f32_e32 v26, v26
	v_rcp_f32_e32 v27, v24
	s_nop 0
	v_pk_mul_f32 v[24:25], v[12:13], v[26:27]
	v_cvt_pk_bf16_f32 v12, v14, v15
	v_cvt_pk_bf16_f32 v13, v20, v21
	v_cvt_pk_bf16_f32 v14, v22, v23
	v_cvt_pk_bf16_f32 v15, v24, v25
	global_store_dwordx4 v[10:11], v[12:15], off offset:32
	s_waitcnt vmcnt(3)
	v_lshlrev_b32_e32 v20, 16, v220
	v_and_b32_e32 v21, 0xffff0000, v220
	v_mul_f32_e32 v12, 0xbfb8aa3b, v20
	v_exp_f32_e32 v12, v12
	v_pk_mul_f32 v[24:25], v[34:35], v[20:21]
	v_add_f32_e32 v12, 1.0, v12
	v_rcp_f32_e32 v22, v12
	v_mul_f32_e32 v12, 0xbfb8aa3b, v21
	v_exp_f32_e32 v12, v12
	s_nop 0
	v_add_f32_e32 v12, 1.0, v12
	v_rcp_f32_e32 v23, v12
	s_nop 0
	v_pk_mul_f32 v[20:21], v[24:25], v[22:23]
	v_lshlrev_b32_e32 v22, 16, v222
	v_mul_f32_e32 v12, 0xbfb8aa3b, v22
	v_exp_f32_e32 v12, v12
	v_and_b32_e32 v23, 0xffff0000, v222
	v_pk_mul_f32 v[18:19], v[18:19], v[22:23]
	v_add_f32_e32 v12, 1.0, v12
	v_rcp_f32_e32 v24, v12
	v_mul_f32_e32 v12, 0xbfb8aa3b, v23
	v_exp_f32_e32 v12, v12
	s_nop 0
	v_add_f32_e32 v12, 1.0, v12
	v_rcp_f32_e32 v25, v12
	v_lshlrev_b32_e32 v12, 16, v221
	v_and_b32_e32 v13, 0xffff0000, v221
	v_mul_f32_e32 v14, 0xbfb8aa3b, v12
	v_pk_mul_f32 v[18:19], v[18:19], v[24:25]
	v_pk_mul_f32 v[24:25], v[32:33], v[12:13]
	v_mul_f32_e32 v12, 0xbfb8aa3b, v13
	v_exp_f32_e32 v12, v12
	v_exp_f32_e32 v14, v14
	v_and_b32_e32 v13, 0xffff0000, v223
	v_add_f32_e32 v12, 1.0, v12
	v_add_f32_e32 v14, 1.0, v14
	v_rcp_f32_e32 v23, v12
	v_lshlrev_b32_e32 v12, 16, v223
	v_rcp_f32_e32 v22, v14
	v_mul_f32_e32 v14, 0xbfb8aa3b, v12
	v_pk_mul_f32 v[2:3], v[2:3], v[12:13]
	v_mul_f32_e32 v12, 0xbfb8aa3b, v13
	v_exp_f32_e32 v14, v14
	v_exp_f32_e32 v12, v12
	v_pk_mul_f32 v[22:23], v[24:25], v[22:23]
	v_add_f32_e32 v14, 1.0, v14
	v_add_f32_e32 v12, 1.0, v12
	v_rcp_f32_e32 v14, v14
	v_rcp_f32_e32 v15, v12
	v_cvt_pk_bf16_f32 v12, v20, v21
	v_cvt_pk_bf16_f32 v13, v22, v23
	v_pk_mul_f32 v[2:3], v[2:3], v[14:15]
	s_nop 0
	v_cvt_pk_bf16_f32 v15, v2, v3
	v_cvt_pk_bf16_f32 v14, v18, v19
	global_store_dwordx4 v[10:11], v[12:15], off offset:64
	s_waitcnt vmcnt(3)
	s_nop 0
	v_lshlrev_b32_e32 v12, 16, v224
	v_and_b32_e32 v13, 0xffff0000, v224
	v_mul_f32_e32 v0, 0xbfb8aa3b, v12
	v_exp_f32_e32 v0, v0
	v_pk_mul_f32 v[16:17], v[16:17], v[12:13]
	v_add_f32_e32 v0, 1.0, v0
	v_rcp_f32_e32 v14, v0
	v_mul_f32_e32 v0, 0xbfb8aa3b, v13
	v_exp_f32_e32 v0, v0
	s_nop 0
	v_add_f32_e32 v0, 1.0, v0
	v_rcp_f32_e32 v15, v0
	s_nop 0
	v_pk_mul_f32 v[12:13], v[16:17], v[14:15]
	v_lshlrev_b32_e32 v14, 16, v226
	v_mul_f32_e32 v0, 0xbfb8aa3b, v14
	v_exp_f32_e32 v0, v0
	v_and_b32_e32 v15, 0xffff0000, v226
	v_pk_mul_f32 v[8:9], v[8:9], v[14:15]
	v_add_f32_e32 v0, 1.0, v0
	v_rcp_f32_e32 v16, v0
	v_mul_f32_e32 v0, 0xbfb8aa3b, v15
	v_exp_f32_e32 v0, v0
	s_nop 0
	v_add_f32_e32 v0, 1.0, v0
	v_rcp_f32_e32 v17, v0
	v_lshlrev_b32_e32 v0, 16, v225
	v_and_b32_e32 v1, 0xffff0000, v225
	v_mul_f32_e32 v2, 0xbfb8aa3b, v0
	v_pk_mul_f32 v[6:7], v[6:7], v[0:1]
	v_mul_f32_e32 v0, 0xbfb8aa3b, v1
	v_exp_f32_e32 v0, v0
	v_exp_f32_e32 v2, v2
	v_and_b32_e32 v1, 0xffff0000, v227
	v_pk_mul_f32 v[8:9], v[8:9], v[16:17]
	v_add_f32_e32 v0, 1.0, v0
	v_add_f32_e32 v2, 1.0, v2
	v_rcp_f32_e32 v15, v0
	v_lshlrev_b32_e32 v0, 16, v227
	v_rcp_f32_e32 v14, v2
	v_mul_f32_e32 v2, 0xbfb8aa3b, v0
	v_pk_mul_f32 v[4:5], v[4:5], v[0:1]
	v_mul_f32_e32 v0, 0xbfb8aa3b, v1
	v_exp_f32_e32 v2, v2
	v_exp_f32_e32 v0, v0
	v_pk_mul_f32 v[6:7], v[6:7], v[14:15]
	v_add_f32_e32 v2, 1.0, v2
	v_add_f32_e32 v0, 1.0, v0
	v_rcp_f32_e32 v2, v2
	v_rcp_f32_e32 v3, v0
	v_cvt_pk_bf16_f32 v0, v12, v13
	v_cvt_pk_bf16_f32 v1, v6, v7
	v_pk_mul_f32 v[4:5], v[4:5], v[2:3]
	v_cvt_pk_bf16_f32 v2, v8, v9
	v_cvt_pk_bf16_f32 v3, v4, v5
	global_store_dwordx4 v[10:11], v[0:3], off offset:96
	s_barrier
	v_mbcnt_lo_u32_b32 v33, -1, 0
	v_mbcnt_hi_u32_b32 v33, -1, v33
	s_nop 0
	v_add_u32_e32 v160, s83, v33
	v_cmp_gt_i32_e32 vcc, s0, v160
	s_and_saveexec_b64 s[4:5], vcc
	s_movk_i32 s8, 0x3eff
	s_cbranch_execz .LBB0_999
	v_readlane_b32 s0, v254, 3
	s_mov_b64 s[6:7], 0
	s_nop 0
	v_add_u32_e32 v0, s0, v33
	v_readlane_b32 s0, v254, 4
	s_nop 1
	v_lshl_add_u32 v1, v33, 2, s0

; #define LAS __attribute__((address_space(3)))
; template <bool HAS_POST, class MaskF>
; __device__ __forceinline__ void attn_run(LAS unsigned char* lds, const bf16* Kg, const bf16* Vg, int pitch, int t0, int t1,
;                                          const bf16x8 (&qr)[4], f32x16& o0, f32x16& o1, f32x16& o2, MaskF& mf, const int wv) {
;     const int tid_ = fresh_tid(wv);
;     const int tid = tid_, lane = tid & 63, r32 = lane & 31, hi = lane >> 5;
;     if (t0 >= t1) return;
;     const int lrow = tid >> 3, lch = tid & 7;
;     const unsigned kwoff = lrow * 144 + lch * 16;
;     const unsigned vwoff = ATT_V0 + lrow * 128 + (((lch >> 1) ^ (((lrow >> 1) & 1) << 1)) * 32) + (lch & 1) * 16;
;     const bf16* kp = Kg + (size_t)(64 * t0 + lrow) * pitch + lch * 8;
;     const bf16* vp = Vg + (size_t)(64 * t0 + lrow) * pitch + lch * 8;
;     const size_t tstride = (size_t)64 * pitch;
;     const v4u z4 = (v4u){0u, 0u, 0u, 0u};
;     v4u kreg0 = *(const v4u*)kp, kreg1 = z4, vreg0 = *(const v4u*)vp, vreg1 = z4;
; __device__ __forceinline__ void nsa_unit(const int wv, LAS unsigned char* lds, int b, int g, int c, const bf16* Y, const bf16* KCMP, const bf16* VCMP, const float* gates, bf16* OG) {
;     ...
;     const int tid = tid_, lane = tid & 63, r32 = lane & 31, hi = lane >> 5, wid = tid >> 6;
;     const int hr = wid >> 1, tq = 32 * (wid & 1) + r32, tabs = 64 * c + tq, hh = 4 * g + hr;
;     LAS float* imph = (LAS float*)(lds + LDS_IMP);
;     LAS unsigned long long* selm = (LAS unsigned long long*)(lds + LDS_SEL);
;     for (int i = tid; i < 4 * 64 * 65; i += NTHREADS) imph[i] = 0.f;
;     __syncthreads();
;     const size_t row = (size_t)b * T + tabs;
;     bf16x8 qr[4]; load_q(Y + row * NSA_LDY + hh * 64, hi, qr);
;     const float* gp = gates + row * 48 + hh * 3; const float g0 = gp[0], g1 = gp[1], g2 = gp[2];
;     f32x16 acc0 = zero16(), acc1 = zero16();
;     LAS float* invl = (LAS float*)(lds + LDS_SEL + 512);
;     {
;         int ncnt = 4 * c + 3; if (ncnt > 255) ncnt = 255; const int nct = (ncnt + 63) >> 6;
;         CmpMask mf; mf.tabs = tabs; mf.hi = hi; mf.imp = imph + (hr * 64 + tq) * 65;
;         const bf16* Kg = KCMP + (size_t)(b * 4 + g) * 256 * 64; const bf16* Vg = VCMP + (size_t)(b * 4 + g) * 256 * 64;
;         f32x16 o0 = zero16(), o1 = zero16(), o2 = zero16();
;         attn_run<true>(lds, Kg, Vg, 64, 0, nct, qr, o0, o1, o2, mf, wv);
.LBB0_999:
	s_or_b64 exec, exec, s[4:5]
	v_lshrrev_b32_e32 v0, 1, v160
	v_and_b32_e32 v2, 31, v33
	v_and_b32_e32 v3, 32, v0
	v_or_b32_e32 v158, v3, v2
	v_readlane_b32 s0, v255, 12
	v_ashrrev_i32_e32 v8, 7, v160
	v_bfe_u32 v159, v33, 5, 1
	v_or_b32_e32 v152, s0, v158
	v_readlane_b32 s0, v254, 21
	v_ashrrev_i32_e32 v153, 31, v152
	v_lshlrev_b32_e32 v114, 4, v159
	v_add_u32_e32 v9, s0, v8
	v_readlane_b32 s0, v254, 9
	v_readlane_b32 s1, v254, 10
	v_lshlrev_b32_e32 v6, 6, v9
	v_ashrrev_i32_e32 v7, 31, v6
	v_lshl_add_u64 v[0:1], s[0:1], 0, v[152:153]
	v_readlane_b32 s0, v254, 27
	v_readlane_b32 s1, v254, 28
	s_waitcnt lgkmcnt(0)
	s_barrier
	v_mov_b64_e32 v[4:5], s[0:1]
	v_mad_u64_u32 v[4:5], s[0:1], v0, s84, v[4:5]
	v_mad_i32_i24 v5, v1, s84, v5
	v_lshl_add_u64 v[4:5], v[6:7], 1, v[4:5]
	v_readlane_b32 s0, v254, 35
	v_lshl_add_u64 v[4:5], v[4:5], 0, v[114:115]
	v_readlane_b32 s1, v254, 36
	global_load_dwordx4 v[116:119], v[4:5], off
	global_load_dwordx4 v[120:123], v[4:5], off offset:32
	global_load_dwordx4 v[124:127], v[4:5], off offset:64
	global_load_dwordx4 v[128:131], v[4:5], off offset:96
	v_add_co_u32_e32 v210, vcc, 0x1000, v4
	s_nop 1
	v_addc_co_u32_e32 v211, vcc, 0, v5, vcc
	global_load_dwordx4 v[212:215], v[210:211], off
	global_load_dwordx4 v[216:219], v[210:211], off offset:32
	global_load_dwordx4 v[220:223], v[210:211], off offset:64
	global_load_dwordx4 v[224:227], v[210:211], off offset:96
	v_mov_b64_e32 v[4:5], s[0:1]
	s_movk_i32 s4, 0xc0
	v_mad_u64_u32 v[4:5], s[0:1], v0, s4, v[4:5]
	v_lshl_add_u32 v0, v9, 1, v9
	v_mad_i32_i24 v5, v1, s4, v5
	v_ashrrev_i32_e32 v1, 31, v0
	v_lshl_add_u64 v[0:1], v[0:1], 2, v[4:5]
	global_load_dwordx3 v[182:184], v[0:1], off
	v_mov_b32_e32 v0, v115
	v_readlane_b32 s0, v254, 60
	v_mov_b32_e32 v0, v115
	v_readlane_b32 s1, v254, 61
	v_lshlrev_b32_e32 v153, 6, v8
	v_mov_b32_e32 v161, v115
	v_mov_b32_e32 v162, v115
	v_mov_b32_e32 v32, v115
	s_mov_b64 s[4:5], -1
	s_and_b64 vcc, exec, s[0:1]
	v_mbcnt_lo_u32_b32 v4, -1, 0
	v_mbcnt_hi_u32_b32 v4, -1, v4
	s_cbranch_vccz .LBB0_1034
	s_lshl_b32 s0, s19, 14
	v_readlane_b32 s1, v254, 39
	s_add_i32 s0, s0, s1
	s_lshl_b32 s4, s0, 1
	v_readlane_b32 s0, v254, 33
	v_add_u32_e32 v5, s83, v4
	s_add_u32 s0, s0, s4
	v_readlane_b32 s1, v254, 34
	s_addc_u32 s1, s1, 0
	v_readlane_b32 s5, v254, 31
	v_ashrrev_i32_e32 v0, 3, v5
	s_add_u32 s4, s5, s4
	v_readlane_b32 s5, v254, 32
	v_ashrrev_i32_e32 v1, 31, v0
	s_addc_u32 s5, s5, 0
	v_and_b32_e32 v6, 7, v4
	v_lshlrev_b64 v[8:9], 7, v[0:1]
	v_lshl_add_u64 v[10:11], s[4:5], 0, v[8:9]
	v_lshlrev_b32_e32 v114, 4, v6
	v_lshl_add_u64 v[154:155], v[10:11], 0, v[114:115]
	v_lshl_add_u64 v[8:9], s[0:1], 0, v[8:9]
	v_lshl_add_u64 v[156:157], v[8:9], 0, v[114:115]
	global_load_dwordx4 v[82:85], v[154:155], off
	global_load_dwordx4 v[86:89], v[156:157], off
	v_readlane_b32 s0, v254, 62
	v_readlane_b32 s1, v254, 63
	s_andn2_b64 vcc, exec, s[0:1]
	s_cbranch_vccnz .LBB0_1002
	v_add_co_u32_e32 v8, vcc, 0x2000, v154
	s_nop 1
	v_addc_co_u32_e32 v9, vcc, 0, v155, vcc
	v_add_co_u32_e32 v10, vcc, 0x2000, v156
	s_nop 1
	v_addc_co_u32_e32 v11, vcc, 0, v157, vcc
	global_load_dwordx4 v[90:93], v[8:9], off
	global_load_dwordx4 v[94:97], v[10:11], off
	s_branch .LBB0_1003

; __device__ __forceinline__ unsigned cvtpk(float lo, float hi) { f32x2_t v = {lo, hi}; bf16x2_t b = __builtin_convertvector(v, bf16x2_t); return __builtin_bit_cast(unsigned, b); }
; __device__ __forceinline__ float sigmoidf_(float x) { return __builtin_amdgcn_rcpf(1.f + fexp2(-1.4426950408889634f * x)); }
; __device__ __forceinline__ float swap_sum(float v) { auto rr = __builtin_amdgcn_permlane32_swap(__float_as_uint(v), __float_as_uint(v), false, false); return __uint_as_float(rr[0]) + __uint_as_float(rr[1]); }
; __device__ __forceinline__ void attn_epilogue(const f32x16& a0, const f32x16& a1, float scale, const bf16* zrow, bf16* orow, int hi) {
; #pragma unroll
;     for (int db = 0; db < 2; ++db)
; #pragma unroll
;         for (int p = 0; p < 2; ++p) {
;             const f32x16& o = db ? a1 : a0;
;             float x[4], y[4];
; #pragma unroll
;             for (int i = 0; i < 4; ++i) {
;                 auto rr = __builtin_amdgcn_permlane32_swap(__float_as_uint(o[8 * p + i]), __float_as_uint(o[8 * p + 4 + i]), false, false);
;                 x[i] = __uint_as_float(rr[0]); y[i] = __uint_as_float(rr[1]);
;             }
;             const int d = 32 * db + 8 * (2 * p + hi);
;             const v4u zz = *(const v4u*)(zrow + d);
;             f32x4 za, zb; unpack8(zz, za, zb);
;             float v[8];
; #pragma unroll
;             for (int i = 0; i < 4; ++i) { v[i] = x[i] * scale * za[i] * sigmoidf_(za[i]); v[4 + i] = y[i] * scale * zb[i] * sigmoidf_(zb[i]); }
;             *(v4u*)(orow + d) = (v4u){cvtpk(v[0], v[1]), cvtpk(v[2], v[3]), cvtpk(v[4], v[5]), cvtpk(v[6], v[7])};
;         }
; }
; __device__ __forceinline__ void moba_unit(const int wv, LAS unsigned char* lds, int b, int h, int qb, const bf16* Y, const float* kmean_l, bf16* OG) {
;     ...
;     const float l = swap_sum(o2[0]); const float il = 1.0f / l;
;     attn_epilogue(o0, o1, il, Y + row * MOBA_LDY + 3072 + h * 64, OG + row * D + h * 64, hi);
.LBB0_1155:
	s_setprio 0
	s_nop 1
	v_mov_b32_e32 v33, v32
	s_nop 1
	v_permlane32_swap_b32_e32 v32, v33
	v_add_f32_e32 v32, v32, v33
	v_div_scale_f32 v33, s[0:1], v32, v32, 1.0
	v_rcp_f32_e32 v34, v33
	v_readlane_b32 s0, v254, 9
	v_readlane_b32 s4, v254, 25
	v_readlane_b32 s1, v254, 10
	v_fma_f32 v35, -v33, v34, 1.0
	v_fmac_f32_e32 v34, v35, v34
	v_div_scale_f32 v35, vcc, 1.0, v32, 1.0
	v_mul_f32_e32 v36, v35, v34
	v_fma_f32 v37, -v33, v36, v35
	v_fmac_f32_e32 v36, v37, v34
	v_fma_f32 v33, -v33, v36, v35
	v_div_fmas_f32 v33, v33, v34, v36
	v_lshlrev_b64 v[36:37], 11, v[112:113]
	v_readlane_b32 s5, v254, 26
	v_lshl_add_u64 v[34:35], v[152:153], 0, s[0:1]
	v_lshlrev_b32_e32 v114, 1, v114
	v_lshl_add_u64 v[36:37], s[4:5], 0, v[36:37]
	v_lshl_add_u64 v[38:39], v[36:37], 0, s[0:1]
	v_lshl_add_u64 v[34:35], v[34:35], 0, v[114:115]
	s_mov_b64 s[0:1], 0x1800
	v_mov_b32_e32 v40, v20
	v_mov_b32_e32 v41, v21
	v_lshl_add_u64 v[20:21], v[34:35], 0, s[0:1]
	s_movk_i32 s0, 0x1000
	v_add_co_u32_e32 v34, vcc, s0, v34
	v_div_fixup_f32 v32, v33, v32, 1.0
	s_nop 0
	v_addc_co_u32_e32 v35, vcc, 0, v35, vcc
	v_permlane32_swap_b32_e32 v16, v40
	v_permlane32_swap_b32_e32 v17, v41
	v_permlane32_swap_b32_e32 v18, v22
	v_permlane32_swap_b32_e32 v19, v23
	s_add_i32 s27, s27, 1
	s_addk_i32 s23, 0x80
	s_cmp_eq_u32 s27, 8
	s_movk_i32 s35, 0x3eff
	s_waitcnt vmcnt(3)
	v_lshlrev_b32_e32 v42, 16, v198
	v_mul_f32_e32 v33, 0xbfb8aa3b, v42
	v_exp_f32_e32 v33, v33
	v_and_b32_e32 v43, 0xffff0000, v198
	v_lshlrev_b32_e32 v34, 16, v199
	v_and_b32_e32 v35, 0xffff0000, v199
	v_add_f32_e32 v33, 1.0, v33
	v_rcp_f32_e32 v44, v33
	v_pk_mul_f32 v[16:17], v[32:33], v[16:17] op_sel_hi:[0,1]
	v_mul_f32_e32 v33, 0xbfb8aa3b, v43
	v_exp_f32_e32 v33, v33
	v_pk_mul_f32 v[16:17], v[16:17], v[42:43]
	v_lshlrev_b32_e32 v42, 16, v200
	v_and_b32_e32 v43, 0xffff0000, v200
	v_add_f32_e32 v33, 1.0, v33
	v_rcp_f32_e32 v45, v33
	v_mul_f32_e32 v33, 0xbfb8aa3b, v42
	v_exp_f32_e32 v33, v33
	v_pk_mul_f32 v[16:17], v[16:17], v[44:45]
	v_add_f32_e32 v33, 1.0, v33
	v_rcp_f32_e32 v44, v33
	v_pk_mul_f32 v[40:41], v[32:33], v[40:41] op_sel_hi:[0,1]
	v_mul_f32_e32 v33, 0xbfb8aa3b, v43
	v_exp_f32_e32 v33, v33
	v_pk_mul_f32 v[40:41], v[40:41], v[42:43]
	v_add_f32_e32 v33, 1.0, v33
	v_rcp_f32_e32 v45, v33
	v_mul_f32_e32 v33, 0xbfb8aa3b, v34
	v_exp_f32_e32 v33, v33
	v_pk_mul_f32 v[40:41], v[40:41], v[44:45]
	v_add_f32_e32 v33, 1.0, v33
	v_rcp_f32_e32 v42, v33
	v_pk_mul_f32 v[18:19], v[32:33], v[18:19] op_sel_hi:[0,1]
	v_mul_f32_e32 v33, 0xbfb8aa3b, v35
	v_exp_f32_e32 v33, v33
	v_pk_mul_f32 v[18:19], v[18:19], v[34:35]
	v_lshlrev_b32_e32 v34, 16, v201
	v_and_b32_e32 v35, 0xffff0000, v201
	v_add_f32_e32 v33, 1.0, v33
	v_rcp_f32_e32 v43, v33
	v_mul_f32_e32 v33, 0xbfb8aa3b, v34
	v_exp_f32_e32 v33, v33
	v_pk_mul_f32 v[18:19], v[18:19], v[42:43]
	v_add_f32_e32 v33, 1.0, v33
	v_rcp_f32_e32 v36, v33
	v_pk_mul_f32 v[22:23], v[32:33], v[22:23] op_sel_hi:[0,1]
	v_mul_f32_e32 v33, 0xbfb8aa3b, v35
	v_exp_f32_e32 v33, v33
	v_pk_mul_f32 v[22:23], v[22:23], v[34:35]
	v_cvt_pk_bf16_f32 v35, v18, v19
	v_mov_b32_e32 v18, v30
	v_add_f32_e32 v33, 1.0, v33
	v_rcp_f32_e32 v37, v33
	v_mov_b32_e32 v19, v31
	v_cvt_pk_bf16_f32 v34, v16, v17
	v_lshl_add_u64 v[16:17], v[38:39], 0, v[114:115]
	v_pk_mul_f32 v[22:23], v[22:23], v[36:37]
	v_cvt_pk_bf16_f32 v36, v40, v41
	v_cvt_pk_bf16_f32 v37, v22, v23
	v_mov_b32_e32 v22, v28
	v_mov_b32_e32 v23, v29
	v_permlane32_swap_b32_e32 v24, v22
	global_store_dwordx4 v[16:17], v[34:37], off
	v_permlane32_swap_b32_e32 v25, v23
	v_pk_mul_f32 v[24:25], v[32:33], v[24:25] op_sel_hi:[0,1]
	v_pk_mul_f32 v[22:23], v[32:33], v[22:23] op_sel_hi:[0,1]
	v_permlane32_swap_b32_e32 v26, v18
	v_permlane32_swap_b32_e32 v27, v19
	v_pk_mul_f32 v[26:27], v[32:33], v[26:27] op_sel_hi:[0,1]
	v_pk_mul_f32 v[18:19], v[32:33], v[18:19] op_sel_hi:[0,1]
	s_waitcnt vmcnt(3)
; __device__ __forceinline__ unsigned cvtpk(float lo, float hi) { f32x2_t v = {lo, hi}; bf16x2_t b = __builtin_convertvector(v, bf16x2_t); return __builtin_bit_cast(unsigned, b); }
; __device__ __forceinline__ float sigmoidf_(float x) { return __builtin_amdgcn_rcpf(1.f + fexp2(-1.4426950408889634f * x)); }
; __device__ __forceinline__ void attn_epilogue(const f32x16& a0, const f32x16& a1, float scale, const bf16* zrow, bf16* orow, int hi) {
; #pragma unroll
;     for (int db = 0; db < 2; ++db)
; #pragma unroll
;         for (int p = 0; p < 2; ++p) {
;             const f32x16& o = db ? a1 : a0;
;             float x[4], y[4];
; #pragma unroll
;             for (int i = 0; i < 4; ++i) {
;                 auto rr = __builtin_amdgcn_permlane32_swap(__float_as_uint(o[8 * p + i]), __float_as_uint(o[8 * p + 4 + i]), false, false);
;                 x[i] = __uint_as_float(rr[0]); y[i] = __uint_as_float(rr[1]);
;             }
;             const int d = 32 * db + 8 * (2 * p + hi);
;             const v4u zz = *(const v4u*)(zrow + d);
;             f32x4 za, zb; unpack8(zz, za, zb);
;             float v[8];
; #pragma unroll
;             for (int i = 0; i < 4; ++i) { v[i] = x[i] * scale * za[i] * sigmoidf_(za[i]); v[4 + i] = y[i] * scale * zb[i] * sigmoidf_(zb[i]); }
;             *(v4u*)(orow + d) = (v4u){cvtpk(v[0], v[1]), cvtpk(v[2], v[3]), cvtpk(v[4], v[5]), cvtpk(v[6], v[7])};
;         }
; }
; __device__ __forceinline__ void moba_unit(const int wv, LAS unsigned char* lds, int b, int h, int qb, const bf16* Y, const float* kmean_l, bf16* OG) {
;     ...
;     __syncthreads();
	v_lshlrev_b32_e32 v34, 16, v202
	v_and_b32_e32 v35, 0xffff0000, v202
	v_mul_f32_e32 v28, 0xbfb8aa3b, v34
	v_exp_f32_e32 v28, v28
	v_pk_mul_f32 v[24:25], v[24:25], v[34:35]
	v_lshlrev_b32_e32 v34, 16, v204
	v_add_f32_e32 v28, 1.0, v28
	v_rcp_f32_e32 v36, v28
	v_mul_f32_e32 v28, 0xbfb8aa3b, v35
	v_exp_f32_e32 v28, v28
	v_and_b32_e32 v35, 0xffff0000, v204
	v_pk_mul_f32 v[22:23], v[22:23], v[34:35]
	v_add_f32_e32 v28, 1.0, v28
	v_rcp_f32_e32 v37, v28
	v_mul_f32_e32 v28, 0xbfb8aa3b, v34
	v_exp_f32_e32 v28, v28
	v_pk_mul_f32 v[24:25], v[24:25], v[36:37]
	v_add_f32_e32 v28, 1.0, v28
	v_rcp_f32_e32 v36, v28
	v_mul_f32_e32 v28, 0xbfb8aa3b, v35
	v_exp_f32_e32 v28, v28
	s_nop 0
	v_add_f32_e32 v28, 1.0, v28
	v_rcp_f32_e32 v37, v28
	s_nop 0
	v_pk_mul_f32 v[34:35], v[22:23], v[36:37]
	v_lshlrev_b32_e32 v22, 16, v203
	v_and_b32_e32 v23, 0xffff0000, v203
	v_mul_f32_e32 v28, 0xbfb8aa3b, v22
	v_pk_mul_f32 v[26:27], v[26:27], v[22:23]
	v_mul_f32_e32 v22, 0xbfb8aa3b, v23
	v_exp_f32_e32 v28, v28
	v_exp_f32_e32 v22, v22
	v_and_b32_e32 v23, 0xffff0000, v205
	v_add_f32_e32 v28, 1.0, v28
	v_add_f32_e32 v22, 1.0, v22
	v_rcp_f32_e32 v28, v28
	v_rcp_f32_e32 v29, v22
	v_lshlrev_b32_e32 v22, 16, v205
	v_pk_mul_f32 v[18:19], v[18:19], v[22:23]
	v_pk_mul_f32 v[26:27], v[26:27], v[28:29]
	v_mul_f32_e32 v28, 0xbfb8aa3b, v22
	v_mul_f32_e32 v22, 0xbfb8aa3b, v23
	v_exp_f32_e32 v28, v28
	v_exp_f32_e32 v22, v22
	v_cvt_pk_bf16_f32 v23, v26, v27
	v_add_f32_e32 v28, 1.0, v28
	v_add_f32_e32 v22, 1.0, v22
	v_rcp_f32_e32 v28, v28
	v_rcp_f32_e32 v29, v22
	v_cvt_pk_bf16_f32 v22, v24, v25
	v_cvt_pk_bf16_f32 v24, v34, v35
	v_pk_mul_f32 v[18:19], v[18:19], v[28:29]
	s_nop 0
	v_cvt_pk_bf16_f32 v25, v18, v19
	global_store_dwordx4 v[16:17], v[22:25], off offset:32
	v_mov_b32_e32 v18, v4
	v_mov_b32_e32 v19, v5
	v_mov_b32_e32 v22, v6
	v_mov_b32_e32 v23, v7
	v_permlane32_swap_b32_e32 v0, v18
	v_permlane32_swap_b32_e32 v1, v19
	v_pk_mul_f32 v[0:1], v[32:33], v[0:1] op_sel_hi:[0,1]
	v_permlane32_swap_b32_e32 v2, v22
	v_permlane32_swap_b32_e32 v3, v23
	v_pk_mul_f32 v[2:3], v[32:33], v[2:3] op_sel_hi:[0,1]
	v_pk_mul_f32 v[18:19], v[32:33], v[18:19] op_sel_hi:[0,1]
	v_pk_mul_f32 v[22:23], v[32:33], v[22:23] op_sel_hi:[0,1]
	s_waitcnt vmcnt(3)
	v_lshlrev_b32_e32 v24, 16, v206
	v_and_b32_e32 v25, 0xffff0000, v206
	v_mul_f32_e32 v4, 0xbfb8aa3b, v24
	v_exp_f32_e32 v4, v4
	v_pk_mul_f32 v[0:1], v[0:1], v[24:25]
	v_lshlrev_b32_e32 v24, 16, v208
	v_add_f32_e32 v4, 1.0, v4
	v_rcp_f32_e32 v26, v4
	v_mul_f32_e32 v4, 0xbfb8aa3b, v25
	v_exp_f32_e32 v4, v4
	v_and_b32_e32 v25, 0xffff0000, v208
	v_pk_mul_f32 v[18:19], v[18:19], v[24:25]
	v_add_f32_e32 v4, 1.0, v4
	v_rcp_f32_e32 v27, v4
	v_mul_f32_e32 v4, 0xbfb8aa3b, v24
	v_exp_f32_e32 v4, v4
	v_pk_mul_f32 v[0:1], v[0:1], v[26:27]
	s_nop 0
	v_cvt_pk_bf16_f32 v0, v0, v1
	v_add_f32_e32 v4, 1.0, v4
	v_rcp_f32_e32 v26, v4
	v_mul_f32_e32 v4, 0xbfb8aa3b, v25
	v_exp_f32_e32 v4, v4
	s_nop 0
	v_add_f32_e32 v4, 1.0, v4
	v_rcp_f32_e32 v27, v4
	v_lshlrev_b32_e32 v4, 16, v207
	v_and_b32_e32 v5, 0xffff0000, v207
	v_mul_f32_e32 v6, 0xbfb8aa3b, v4
	v_pk_mul_f32 v[2:3], v[2:3], v[4:5]
	v_mul_f32_e32 v4, 0xbfb8aa3b, v5
	v_exp_f32_e32 v4, v4
	v_exp_f32_e32 v6, v6
	v_and_b32_e32 v5, 0xffff0000, v209
	v_pk_mul_f32 v[18:19], v[18:19], v[26:27]
	v_add_f32_e32 v4, 1.0, v4
	v_add_f32_e32 v6, 1.0, v6
	v_rcp_f32_e32 v25, v4
	v_lshlrev_b32_e32 v4, 16, v209
	v_rcp_f32_e32 v24, v6
	v_mul_f32_e32 v6, 0xbfb8aa3b, v4
	v_pk_mul_f32 v[22:23], v[22:23], v[4:5]
	v_mul_f32_e32 v4, 0xbfb8aa3b, v5
	v_exp_f32_e32 v6, v6
	v_exp_f32_e32 v4, v4
	v_pk_mul_f32 v[2:3], v[2:3], v[24:25]
	v_add_f32_e32 v6, 1.0, v6
	v_add_f32_e32 v4, 1.0, v4
	v_rcp_f32_e32 v6, v6
	v_rcp_f32_e32 v7, v4
	v_cvt_pk_bf16_f32 v1, v2, v3
	v_cvt_pk_bf16_f32 v2, v18, v19
	v_pk_mul_f32 v[4:5], v[22:23], v[6:7]
	s_nop 0
	v_cvt_pk_bf16_f32 v3, v4, v5
	global_store_dwordx4 v[16:17], v[0:3], off offset:64
	v_mov_b32_e32 v6, v12
	v_mov_b32_e32 v7, v13
	v_mov_b32_e32 v4, v14
	v_permlane32_swap_b32_e32 v8, v6
	v_permlane32_swap_b32_e32 v9, v7
	v_pk_mul_f32 v[8:9], v[32:33], v[8:9] op_sel_hi:[0,1]
	v_mov_b32_e32 v5, v15
	v_permlane32_swap_b32_e32 v10, v4
	s_nop 0
	v_permlane32_swap_b32_e32 v11, v5
	v_pk_mul_f32 v[10:11], v[32:33], v[10:11] op_sel_hi:[0,1]
	v_pk_mul_f32 v[6:7], v[32:33], v[6:7] op_sel_hi:[0,1]
	v_pk_mul_f32 v[4:5], v[32:33], v[4:5] op_sel_hi:[0,1]
	s_waitcnt vmcnt(3)
	v_lshlrev_b32_e32 v12, 16, v210
	v_and_b32_e32 v13, 0xffff0000, v210
	v_mul_f32_e32 v0, 0xbfb8aa3b, v12
	v_exp_f32_e32 v0, v0
	v_pk_mul_f32 v[8:9], v[8:9], v[12:13]
	v_lshlrev_b32_e32 v12, 16, v212
	v_add_f32_e32 v0, 1.0, v0
	v_rcp_f32_e32 v14, v0
	v_mul_f32_e32 v0, 0xbfb8aa3b, v13
	v_exp_f32_e32 v0, v0
	v_and_b32_e32 v13, 0xffff0000, v212
	v_pk_mul_f32 v[6:7], v[6:7], v[12:13]
	v_add_f32_e32 v0, 1.0, v0
	v_rcp_f32_e32 v15, v0
	v_mul_f32_e32 v0, 0xbfb8aa3b, v12
	v_exp_f32_e32 v0, v0
	v_pk_mul_f32 v[8:9], v[8:9], v[14:15]
	v_add_f32_e32 v0, 1.0, v0
	v_rcp_f32_e32 v14, v0
	v_mul_f32_e32 v0, 0xbfb8aa3b, v13
	v_exp_f32_e32 v0, v0
	s_nop 0
	v_add_f32_e32 v0, 1.0, v0
	v_rcp_f32_e32 v15, v0
	v_lshlrev_b32_e32 v0, 16, v211
	v_and_b32_e32 v1, 0xffff0000, v211
	v_mul_f32_e32 v2, 0xbfb8aa3b, v0
	v_pk_mul_f32 v[10:11], v[10:11], v[0:1]
	v_mul_f32_e32 v0, 0xbfb8aa3b, v1
	v_exp_f32_e32 v0, v0
	v_exp_f32_e32 v2, v2
	v_and_b32_e32 v1, 0xffff0000, v213
	v_pk_mul_f32 v[6:7], v[6:7], v[14:15]
	v_add_f32_e32 v0, 1.0, v0
	v_add_f32_e32 v2, 1.0, v2
	v_rcp_f32_e32 v13, v0
	v_lshlrev_b32_e32 v0, 16, v213
	v_rcp_f32_e32 v12, v2
	v_mul_f32_e32 v2, 0xbfb8aa3b, v0
	v_pk_mul_f32 v[4:5], v[4:5], v[0:1]
	v_mul_f32_e32 v0, 0xbfb8aa3b, v1
	v_exp_f32_e32 v2, v2
	v_exp_f32_e32 v0, v0
	v_pk_mul_f32 v[10:11], v[10:11], v[12:13]
	v_add_f32_e32 v2, 1.0, v2
	v_add_f32_e32 v0, 1.0, v0
	v_rcp_f32_e32 v2, v2
	v_rcp_f32_e32 v3, v0
	v_cvt_pk_bf16_f32 v0, v8, v9
	v_cvt_pk_bf16_f32 v1, v10, v11
	v_pk_mul_f32 v[4:5], v[4:5], v[2:3]
	v_cvt_pk_bf16_f32 v2, v6, v7
	v_cvt_pk_bf16_f32 v3, v4, v5
	global_store_dwordx4 v[16:17], v[0:3], off offset:96
	s_barrier
	s_cbranch_scc1 .LBB0_1207

; __device__ __forceinline__ void moba_unit(const int wv, LAS unsigned char* lds, int b, int h, int qb, const bf16* Y, const float* kmean_l, bf16* OG) {
;     ...
;         for (int it = 0; it < 3; ++it) {
;             float best = -3.0e38f; int bi = -1;
; #pragma unroll
;             for (int n = 0; n < 16; ++n) { const bool ok = (n < qb) && !((mask >> n) & 1u); const float cand = ok ? ga[n] : -3.0e38f; if (cand > best) { best = cand; bi = n; } }
;             if (bi >= 0) mask |= (1u << bi);
;         }
.LBB0_1159:
	v_and_b32_e32 v18, 1, v17
	v_cmp_eq_u32_e64 s[6:7], 0, v18
	s_and_b64 s[6:7], s[4:5], s[6:7]
	v_and_b32_e32 v20, 2, v17
	v_cndmask_b32_e64 v18, v245, v1, s[6:7]
	v_cmp_nlt_f32_e64 s[6:7], s1, v18
	s_add_i32 s0, s0, -1
	s_nop 0
	v_cndmask_b32_e64 v18, v18, v245, s[6:7]
	v_cndmask_b32_e64 v19, 0, -1, s[6:7]
	v_cmp_eq_u32_e64 s[6:7], 0, v20
	s_and_b64 s[6:7], s[14:15], s[6:7]
	s_nop 0
	v_cndmask_b32_e64 v20, v245, v7, s[6:7]
	v_cmp_gt_f32_e64 s[6:7], v20, v18
	s_nop 1
	v_cndmask_b32_e64 v18, v18, v20, s[6:7]
	v_and_b32_e32 v20, 4, v17
	v_cndmask_b32_e64 v19, v19, 1, s[6:7]
	v_cmp_eq_u32_e64 s[6:7], 0, v20
	s_and_b64 s[6:7], s[16:17], s[6:7]
	s_nop 0
	v_cndmask_b32_e64 v20, v245, v11, s[6:7]
	v_cmp_gt_f32_e64 s[6:7], v20, v18
	s_nop 1
	v_cndmask_b32_e64 v18, v18, v20, s[6:7]
	v_and_b32_e32 v20, 8, v17
	v_cndmask_b32_e64 v19, v19, 2, s[6:7]
	v_cmp_eq_u32_e64 s[6:7], 0, v20
	s_and_b64 s[6:7], s[18:19], s[6:7]
	s_nop 0
	v_cndmask_b32_e64 v20, v245, v13, s[6:7]
	v_cmp_gt_f32_e64 s[6:7], v20, v18
	s_nop 1
	v_cndmask_b32_e64 v18, v18, v20, s[6:7]
	v_and_b32_e32 v20, 16, v17
	v_cndmask_b32_e64 v19, v19, 3, s[6:7]
	v_cmp_eq_u32_e64 s[6:7], 0, v20
	s_and_b64 s[6:7], s[20:21], s[6:7]
	s_nop 0
	v_cndmask_b32_e64 v20, v245, v14, s[6:7]
	v_cmp_gt_f32_e64 s[6:7], v20, v18
	s_nop 1
	v_cndmask_b32_e64 v18, v18, v20, s[6:7]
	v_and_b32_e32 v20, 32, v17
	v_cndmask_b32_e64 v19, v19, 4, s[6:7]
	v_cmp_eq_u32_e64 s[6:7], 0, v20
	s_and_b64 s[6:7], s[30:31], s[6:7]
	s_nop 0
	v_cndmask_b32_e64 v20, v245, v15, s[6:7]
	v_cmp_gt_f32_e64 s[6:7], v20, v18
	s_nop 1
	v_cndmask_b32_e64 v18, v18, v20, s[6:7]
	v_and_b32_e32 v20, 64, v17
	v_cndmask_b32_e64 v19, v19, 5, s[6:7]
	v_cmp_eq_u32_e64 s[6:7], 0, v20
	s_and_b64 s[6:7], s[38:39], s[6:7]
	s_nop 0
	v_cndmask_b32_e64 v20, v245, v16, s[6:7]
	v_cmp_gt_f32_e64 s[6:7], v20, v18
	s_nop 1
	v_cndmask_b32_e64 v18, v18, v20, s[6:7]
	v_and_b32_e32 v20, 0x80, v17
	v_cndmask_b32_e64 v19, v19, 6, s[6:7]
	v_cmp_eq_u32_e64 s[6:7], 0, v20
	s_and_b64 s[6:7], s[40:41], s[6:7]
	s_nop 0
	v_cndmask_b32_e64 v20, v245, v3, s[6:7]
	v_cmp_gt_f32_e64 s[6:7], v20, v18
	s_nop 1
	v_cndmask_b32_e64 v18, v18, v20, s[6:7]
	v_and_b32_e32 v20, 0x100, v17
	v_cndmask_b32_e64 v19, v19, 7, s[6:7]
	v_cmp_eq_u32_e64 s[6:7], 0, v20
	s_and_b64 s[6:7], s[42:43], s[6:7]
	s_nop 0
	v_cndmask_b32_e64 v20, v245, v6, s[6:7]
	v_cmp_gt_f32_e64 s[6:7], v20, v18
	s_nop 1
	v_cndmask_b32_e64 v18, v18, v20, s[6:7]
	v_and_b32_e32 v20, 0x200, v17
	v_cndmask_b32_e64 v19, v19, 8, s[6:7]
	v_cmp_eq_u32_e64 s[6:7], 0, v20
	s_and_b64 s[6:7], s[44:45], s[6:7]
	s_nop 0
	v_cndmask_b32_e64 v20, v245, v10, s[6:7]
	v_cmp_gt_f32_e64 s[6:7], v20, v18
	s_nop 1
	v_cndmask_b32_e64 v18, v18, v20, s[6:7]
	v_and_b32_e32 v20, 0x400, v17
	v_cndmask_b32_e64 v19, v19, 9, s[6:7]
	v_cmp_eq_u32_e64 s[6:7], 0, v20
	s_and_b64 s[6:7], s[46:47], s[6:7]
	s_nop 0
	v_cndmask_b32_e64 v20, v245, v8, s[6:7]
	v_cmp_gt_f32_e64 s[6:7], v20, v18
	s_nop 1
	v_cndmask_b32_e64 v18, v18, v20, s[6:7]
	v_and_b32_e32 v20, 0x800, v17
	v_cndmask_b32_e64 v19, v19, 10, s[6:7]
	v_cmp_eq_u32_e64 s[6:7], 0, v20
	s_and_b64 s[6:7], s[48:49], s[6:7]
	s_nop 0
	v_cndmask_b32_e64 v20, v245, v9, s[6:7]
	v_cmp_gt_f32_e64 s[6:7], v20, v18
	s_nop 1
	v_cndmask_b32_e64 v18, v18, v20, s[6:7]
	v_and_b32_e32 v20, 0x1000, v17
	v_cndmask_b32_e64 v19, v19, 11, s[6:7]
	v_cmp_eq_u32_e64 s[6:7], 0, v20
	s_and_b64 s[6:7], s[50:51], s[6:7]
	s_nop 0
	v_cndmask_b32_e64 v20, v245, v4, s[6:7]
	v_cmp_gt_f32_e64 s[6:7], v20, v18
	s_nop 1
	v_cndmask_b32_e64 v18, v18, v20, s[6:7]
	v_and_b32_e32 v20, 0x2000, v17
	v_cndmask_b32_e64 v19, v19, 12, s[6:7]
	v_cmp_eq_u32_e64 s[6:7], 0, v20
	s_and_b64 s[6:7], s[52:53], s[6:7]
	s_nop 0
	v_cndmask_b32_e64 v20, v245, v5, s[6:7]
	v_cmp_gt_f32_e64 s[6:7], v20, v18
	s_nop 1
	v_cndmask_b32_e64 v18, v18, v20, s[6:7]
	v_and_b32_e32 v20, 0x4000, v17
	v_cndmask_b32_e64 v19, v19, 13, s[6:7]
	v_cmp_eq_u32_e64 s[6:7], 0, v20
	s_and_b64 s[6:7], s[54:55], s[6:7]
	s_cmp_lg_u32 s0, 0
	v_cndmask_b32_e64 v20, v245, v2, s[6:7]
	v_cmp_gt_f32_e64 s[6:7], v20, v18
	s_nop 1
	v_cndmask_b32_e64 v18, v18, v20, s[6:7]
	v_cndmask_b32_e64 v19, v19, 14, s[6:7]
	v_cmp_ngt_f32_e64 s[6:7], s1, v18
	s_nop 1
	v_cndmask_b32_e64 v18, 15, v19, s[6:7]
	v_lshlrev_b32_e64 v19, v18, 1
	v_cmp_lt_i32_e64 s[6:7], -1, v18
	s_nop 1
	v_cndmask_b32_e64 v18, 0, v19, s[6:7]
	v_or_b32_e32 v17, v18, v17
	s_cbranch_scc1 .LBB0_1159
; #define LAS __attribute__((address_space(3)))
; template <bool HAS_POST, class MaskF>
; __device__ __forceinline__ void attn_run(LAS unsigned char* lds, const bf16* Kg, const bf16* Vg, int pitch, int t0, int t1,
;                                          const bf16x8 (&qr)[4], f32x16& o0, f32x16& o1, f32x16& o2, MaskF& mf, const int wv) {
;     ...
;     const int lrow = tid >> 3, lch = tid & 7;
;     const unsigned kwoff = lrow * 144 + lch * 16;
;     const unsigned vwoff = ATT_V0 + lrow * 128 + (((lch >> 1) ^ (((lrow >> 1) & 1) << 1)) * 32) + (lch & 1) * 16;
;     const bf16* kp = Kg + (size_t)(64 * t0 + lrow) * pitch + lch * 8;
;     const bf16* vp = Vg + (size_t)(64 * t0 + lrow) * pitch + lch * 8;
;     const size_t tstride = (size_t)64 * pitch;
;     const v4u z4 = (v4u){0u, 0u, 0u, 0u};
;     v4u kreg0 = *(const v4u*)kp, kreg1 = z4, vreg0 = *(const v4u*)vp, vreg1 = z4;
;     if (t0 + 1 < t1) { kreg1 = *(const v4u*)(kp + tstride); vreg1 = *(const v4u*)(vp + tstride); }
;     *(LAS v4u*)(lds + kwoff) = kreg0; *(LAS v4u*)(lds + KBUF + kwoff) = kreg1;
;     *(LAS v4u*)(lds + vwoff) = vreg0; *(LAS v4u*)(lds + VBUF + vwoff) = vreg1;
;     __syncthreads();
;     ACtx cx; cx.lds = lds; cx.kroff = r32 * 144 + hi * 16;
;     { const int gi = lane & 15, dsub = (lane >> 4) & 1, q4 = gi >> 2;
;       cx.vro0 = ATT_V0 + (4 * hi + q4) * 128 + (((0 + dsub) ^ (q4 & 2)) * 32) + (gi & 3) * 8;
;       cx.vro1 = ATT_V0 + (4 * hi + q4) * 128 + (((2 + dsub) ^ (q4 & 2)) * 32) + (gi & 3) * 8; }
;     if (wv >= 4) __builtin_amdgcn_s_setprio(1);
; __device__ __forceinline__ void moba_unit(const int wv, LAS unsigned char* lds, int b, int h, int qb, const bf16* Y, const float* kmean_l, bf16* OG) {
;     ...
;         if (half == 0) selm[ql] = mask;
;     }
;     __syncthreads();
;     MobaMask mf; mf.qb = qb; mf.qrel = 32 * wid + r32; mf.hi = hi; mf.wq0 = 32 * wv; mf.sel = selm[32 * wid + r32];
;     const size_t row = rowblk + 32 * wid + r32;
;     bf16x8 qr[4]; load_q(Y + row * MOBA_LDY + h * 64, hi, qr);
;     f32x16 o0 = zero16(), o1 = zero16(), o2 = zero16();
;     const bf16* Kg = Y + (size_t)b * T * MOBA_LDY + 1024 + h * 64;
;     attn_run<false>(lds, Kg, Kg + 1024, MOBA_LDY, 0, 4 * qb + 4, qr, o0, o1, o2, mf, wv);
	s_and_saveexec_b64 s[4:5], vcc
	v_lshl_add_u32 v1, v0, 2, 0
	v_add_u32_e32 v1, 0x21400, v1
	ds_write_b32 v1, v17
	s_or_b64 exec, exec, s[4:5]
	v_and_b32_e32 v2, 0xffffffe0, v0
	s_movk_i32 s1, 0xffe0
	v_bfi_b32 v158, s1, v0, v12
	v_ashrrev_i32_e32 v3, 31, v2
	v_and_b32_e32 v1, 31, v12
	v_lshl_add_u32 v0, v158, 2, 0
	v_lshl_add_u64 v[112:113], s[10:11], 0, v[2:3]
	s_lshl_b32 s0, s12, 6
	v_add_u32_e32 v0, 0x21400, v0
	v_or_b32_e32 v112, v112, v1
	v_readlane_b32 s6, v254, 27
	s_and_b32 s0, s0, 0x3c0
	s_waitcnt lgkmcnt(0)
	s_barrier
	ds_read_b32 v159, v0
	v_lshlrev_b64 v[0:1], 13, v[112:113]
	v_readlane_b32 s7, v254, 28
	v_readlane_b32 s4, v254, 9
	v_bfe_u32 v48, v12, 5, 1
	v_lshl_add_u64 v[152:153], s[6:7], 0, v[0:1]
	v_readlane_b32 s5, v254, 10
	s_lshl_b32 s4, s0, 1
	v_lshlrev_b32_e32 v114, 4, v48
	v_lshl_add_u64 v[0:1], v[152:153], 0, s[4:5]
	v_lshl_add_u64 v[0:1], v[0:1], 0, v[114:115]
	global_load_dwordx4 v[80:83], v[0:1], off
	global_load_dwordx4 v[84:87], v[0:1], off offset:32
	global_load_dwordx4 v[88:91], v[0:1], off offset:64
	global_load_dwordx4 v[92:95], v[0:1], off offset:96
	v_add_co_u32_e32 v172, vcc, 0x1800, v0
	s_nop 1
	v_addc_co_u32_e32 v173, vcc, 0, v1, vcc
	global_load_dwordx4 v[198:201], v[172:173], off
	global_load_dwordx4 v[202:205], v[172:173], off offset:32
	global_load_dwordx4 v[206:209], v[172:173], off offset:64
	global_load_dwordx4 v[210:213], v[172:173], off offset:96
	v_mov_b32_e32 v16, v115
	v_mov_b32_e32 v0, v115
	v_mov_b32_e32 v32, v115
	s_lshl_b64 s[0:1], s[8:9], 25
	v_mbcnt_lo_u32_b32 v49, -1, 0
	v_mbcnt_hi_u32_b32 v49, -1, v49
	s_add_u32 s0, s6, s0
	v_bfe_u32 v3, v49, 1, 2
	v_lshrrev_b32_e32 v4, 3, v49
	v_add_u32_e32 v50, s83, v49
	v_bitop3_b32 v3, v3, v4, 2 bitop3:0x78
	s_addc_u32 s1, s7, s1
	v_writelane_b32 v254, s4, 9
	v_ashrrev_i32_e32 v2, 3, v50
	v_lshlrev_b32_e32 v7, 5, v3
	v_lshlrev_b32_e32 v3, 4, v49
	v_writelane_b32 v254, s5, 10
	s_add_u32 s0, s0, s4
	v_and_b32_e32 v1, 7, v49
	s_movk_i32 s4, 0x90
	v_and_b32_e32 v8, 16, v3
	v_ashrrev_i32_e32 v3, 31, v2
	s_addc_u32 s1, s1, 0
	v_mul_lo_u32 v6, v2, s4
	v_lshlrev_b32_e32 v114, 4, v1
	v_lshlrev_b32_e32 v1, 7, v2
	v_lshlrev_b64 v[2:3], 13, v[2:3]
	v_lshl_add_u64 v[2:3], s[0:1], 0, v[2:3]
	v_lshl_add_u64 v[2:3], v[2:3], 0, v[114:115]
	s_mov_b64 s[0:1], 0x800
	v_lshl_add_u64 v[154:155], v[2:3], 0, s[0:1]
	s_mov_b32 s0, 0x80000
	v_add_co_u32_e32 v4, vcc, s0, v2
	s_mov_b32 s0, 0x81000
	s_nop 0
	v_addc_co_u32_e32 v5, vcc, 0, v3, vcc
	global_load_dwordx4 v[96:99], v[2:3], off offset:2048
	global_load_dwordx4 v[100:103], v[154:155], off offset:2048
	v_add_co_u32_e32 v2, vcc, s0, v2
	global_load_dwordx4 v[104:107], v[4:5], off offset:2048
	s_nop 0
	v_addc_co_u32_e32 v3, vcc, 0, v3, vcc
	global_load_dwordx4 v[108:111], v[2:3], off
	v_readlane_b32 s0, v253, 63
	v_or3_b32 v1, v1, v7, v8
	v_readlane_b32 s1, v254, 0
	v_add3_u32 v160, v6, v114, 0
	v_add_u32_e32 v161, 0, v1
	s_andn2_b64 vcc, exec, s[0:1]
	s_waitcnt vmcnt(3)
	ds_write_b128 v160, v[96:99]
	s_waitcnt vmcnt(1)
	ds_write_b128 v160, v[104:107] offset:9216
	ds_write_b128 v161, v[100:103] offset:36864
	s_waitcnt vmcnt(0)
	ds_write_b128 v161, v[108:111] offset:45056
	s_waitcnt lgkmcnt(0)
	s_barrier
	s_cbranch_vccnz .LBB0_1164
	s_setprio 1
